# attention: next unit's first K/V tiles and Q prefetched during the last two key tiles (merge buffers moved, +16 KB static LDS)
# speedup vs baseline: 1.0037x; 1.0037x over previous
.LBB0_625:
	s_add_u32 s4, s0, s14
	s_addc_u32 s5, s1, s15
	global_load_dwordx4 v[4:7], v193, s[4:5] offset:48
	global_load_dwordx4 v[8:11], v193, s[4:5] offset:32
	global_load_dwordx4 v[12:15], v193, s[4:5] offset:16
	global_load_dwordx4 v[16:19], v193, s[4:5]
	global_load_dwordx4 v[20:23], v193, s[4:5] offset:304
	global_load_dwordx4 v[24:27], v193, s[4:5] offset:288
	global_load_dwordx4 v[28:31], v193, s[4:5] offset:272
	global_load_dwordx4 v[32:35], v193, s[4:5] offset:256
	global_load_dwordx4 v[36:39], v193, s[4:5] offset:560
	global_load_dwordx4 v[40:43], v193, s[4:5] offset:544
	global_load_dwordx4 v[44:47], v193, s[4:5] offset:528
	global_load_dwordx4 v[48:51], v193, s[4:5] offset:512
	global_load_dwordx4 v[52:55], v193, s[4:5] offset:816
	global_load_dwordx4 v[56:59], v193, s[4:5] offset:800
	global_load_dwordx4 v[60:63], v193, s[4:5] offset:784
	global_load_dwordx4 v[64:67], v193, s[4:5] offset:768
	s_add_u32 s14, s14, 64
	s_addc_u32 s15, s15, 0
	s_cmpk_eq_i32 s14, 0x100
	s_waitcnt vmcnt(12)
	v_mov_b32_e32 v68, v16
	v_mov_b32_e32 v16, v18
	s_waitcnt vmcnt(9)
	v_mov_b32_e32 v18, v28
	s_waitcnt vmcnt(8)
	v_mov_b32_e32 v70, v32
	v_mov_b32_e32 v32, v34
	s_waitcnt vmcnt(4)
	v_mov_b32_e32 v69, v48
	v_mov_b32_e32 v48, v17
	v_mov_b32_e32 v17, v50
	v_mov_b32_e32 v50, v19
	s_waitcnt vmcnt(0)
	v_mov_b32_e32 v71, v64
	v_pk_fma_f32 v[0:1], v[68:69], v[70:71], v[0:1]
	v_mov_b32_e32 v64, v33
	v_pk_fma_f32 v[0:1], v[48:49], v[64:65], v[0:1]
	v_mov_b32_e32 v33, v66
	v_pk_fma_f32 v[0:1], v[16:17], v[32:33], v[0:1]
	v_mov_b32_e32 v66, v35
	v_pk_fma_f32 v[0:1], v[50:51], v[66:67], v[0:1]
	v_mov_b32_e32 v16, v12
	v_mov_b32_e32 v17, v44
	v_mov_b32_e32 v19, v60
	v_pk_fma_f32 v[0:1], v[16:17], v[18:19], v[0:1]
	v_mov_b32_e32 v44, v13
	v_mov_b32_e32 v60, v29
	v_pk_fma_f32 v[0:1], v[44:45], v[60:61], v[0:1]
	v_mov_b32_e32 v12, v14
	v_mov_b32_e32 v13, v46
	v_mov_b32_e32 v16, v30
	v_mov_b32_e32 v17, v62
	v_pk_fma_f32 v[0:1], v[12:13], v[16:17], v[0:1]
	v_mov_b32_e32 v46, v15
	v_mov_b32_e32 v62, v31
	v_pk_fma_f32 v[0:1], v[46:47], v[62:63], v[0:1]
	v_mov_b32_e32 v12, v8
	v_mov_b32_e32 v13, v40
	v_mov_b32_e32 v14, v24
	v_mov_b32_e32 v15, v56
	v_pk_fma_f32 v[0:1], v[12:13], v[14:15], v[0:1]
	v_mov_b32_e32 v40, v9
	v_mov_b32_e32 v56, v25
	v_pk_fma_f32 v[0:1], v[40:41], v[56:57], v[0:1]
	v_mov_b32_e32 v8, v10
	v_mov_b32_e32 v9, v42
	v_mov_b32_e32 v12, v26
	v_mov_b32_e32 v13, v58
	v_pk_fma_f32 v[0:1], v[8:9], v[12:13], v[0:1]
	v_mov_b32_e32 v42, v11
	v_mov_b32_e32 v58, v27
	v_pk_fma_f32 v[0:1], v[42:43], v[58:59], v[0:1]
	v_mov_b32_e32 v8, v4
	v_mov_b32_e32 v9, v36
	v_mov_b32_e32 v10, v20
	v_mov_b32_e32 v11, v52
	v_pk_fma_f32 v[0:1], v[8:9], v[10:11], v[0:1]
	v_mov_b32_e32 v36, v5
	v_mov_b32_e32 v52, v21
	v_pk_fma_f32 v[0:1], v[36:37], v[52:53], v[0:1]
	v_mov_b32_e32 v4, v6
	v_mov_b32_e32 v5, v38
	v_mov_b32_e32 v8, v22
	v_mov_b32_e32 v9, v54
	v_pk_fma_f32 v[0:1], v[4:5], v[8:9], v[0:1]
	v_mov_b32_e32 v38, v7
	v_mov_b32_e32 v54, v23
	v_pk_fma_f32 v[0:1], v[38:39], v[54:55], v[0:1]
	s_cbranch_scc0 .LBB0_625
	v_readfirstlane_b32 s0, v3
	s_cmpk_gt_i32 s0, 0x3ff
	s_cbranch_scc1 .LBB0_654
	v_readlane_b32 s14, v252, 1
	s_mov_b32 s1, 0x3fb8aa3b
	s_mov_b32 s4, 0xc2ce8ed0
	v_cvt_f32_u32_e32 v3, s14
	s_mov_b32 s5, 0x42b17218
	s_add_u32 s6, s6, 0x5720000
	s_addc_u32 s7, s7, 0
	v_mul_f32_e32 v3, 0xbe99999a, v3
	v_mul_f32_e32 v4, 0x3fb8aa3b, v3
	v_fma_f32 v5, v3, s1, -v4
	v_rndne_f32_e32 v6, v4
	v_fmac_f32_e32 v5, 0x32a5705f, v3
	v_sub_f32_e32 v4, v4, v6
	v_add_f32_e32 v4, v4, v5
	v_cvt_i32_f32_e32 v6, v6
	v_exp_f32_e32 v4, v4
	v_cmp_ngt_f32_e32 vcc, s4, v3
	s_add_u32 s10, s10, 0x9b20000
	s_addc_u32 s11, s11, 0
	v_ldexp_f32 v4, v4, v6
	v_cndmask_b32_e32 v4, 0, v4, vcc
	v_cmp_nlt_f32_e32 vcc, s5, v3
	v_readlane_b32 s15, v252, 2
	s_add_u32 s12, s12, 0x3700000
	v_cndmask_b32_e32 v3, v241, v4, vcc
	v_mul_f32_e32 v4, 0x3fb8aa3b, v0
	v_rndne_f32_e32 v5, v4
	v_sub_f32_e32 v6, v4, v5
	v_fma_f32 v4, v0, s1, -v4
	v_fmac_f32_e32 v4, 0x32a5705f, v0
	v_add_f32_e32 v4, v6, v4
	v_exp_f32_e32 v4, v4
	v_cvt_i32_f32_e32 v5, v5
	v_cmp_ngt_f32_e32 vcc, s4, v0
	s_addc_u32 s13, s13, 0
	s_ashr_i32 s28, s2, 8
	v_ldexp_f32 v4, v4, v5
	v_mul_f32_e32 v5, 0x3fb8aa3b, v1
	v_rndne_f32_e32 v6, v5
	v_sub_f32_e32 v7, v5, v6
	v_fma_f32 v5, v1, s1, -v5
	v_fmac_f32_e32 v5, 0x32a5705f, v1
	v_add_f32_e32 v5, v7, v5
	v_exp_f32_e32 v5, v5
	v_cvt_i32_f32_e32 v6, v6
	v_cndmask_b32_e32 v4, 0, v4, vcc
	v_cmp_nlt_f32_e32 vcc, s5, v0
	s_ashr_i32 s16, s2, 6
	v_fmamk_f32 v3, v3, 0xbf19999a, v239
	v_cndmask_b32_e32 v0, v241, v4, vcc
	v_ldexp_f32 v4, v5, v6
	v_cmp_ngt_f32_e32 vcc, s4, v1
	v_sub_f32_e32 v176, 1.0, v3
	v_and_b32_e32 v7, 63, v2
	v_cndmask_b32_e32 v4, 0, v4, vcc
	v_cmp_nlt_f32_e32 vcc, s5, v1
	s_lshl_b64 s[4:5], s[14:15], 9
	s_add_u32 s26, s42, s4
	s_addc_u32 s27, s43, s5
	s_lshl_b32 s1, s0, 1
	s_and_b32 s1, s1, 14
	s_ashr_i32 s4, s0, 7
	s_lshl_b32 s14, s28, 6
	s_lshl_b32 s5, s16, 10
	v_cndmask_b32_e32 v1, v241, v4, vcc
	s_and_b32 s30, s16, 3
	s_add_i32 s1, s1, s4
	s_lshr_b32 s4, s0, 3
	s_ashr_i32 s15, s14, 31
	s_add_i32 s5, s5, 0
	v_sub_f32_e32 v0, v0, v1
	s_cmpk_lt_u32 s2, 0x100
	v_add_f32_e32 v177, v3, v0
	v_lshrrev_b32_e32 v3, 1, v2
	v_lshlrev_b32_e32 v0, 1, v2
	s_cselect_b64 s[16:17], -1, 0
	s_lshl_b32 s2, s28, 13
	v_and_b32_e32 v0, 8, v0
	v_and_b32_e32 v4, 19, v2
	v_and_b32_e32 v6, 4, v3
	s_add_i32 s2, s2, 0
	v_and_b32_e32 v1, 31, v2
	v_or3_b32 v4, v0, v4, v6
	s_cmp_eq_u32 s28, 1
	v_lshl_or_b32 v178, s30, 5, v1
	v_lshl_add_u32 v179, v4, 7, s2
	s_cselect_b64 s[28:29], -1, 0
	v_lshlrev_b32_e32 v1, 7, v1
	s_add_i32 s2, 0, 0x1c000
	v_add_u32_e32 v180, s2, v1
	s_mov_b32 s2, 0xc000
	s_cmp_eq_u32 s30, 1
	s_cselect_b32 s2, 0x8000, s2
	s_cmp_eq_u32 s30, 2
	s_cselect_b32 s2, 0x14000, s2
	s_cmp_eq_u32 s30, 3
	s_cselect_b32 s2, 0x20010, s2
	v_lshrrev_b32_e32 v6, 1, v4
	v_bfe_u32 v8, v2, 5, 1
	s_add_i32 s2, s2, 0
	v_lshl_add_u32 v181, v7, 2, s2
	v_bitop3_b32 v7, v6, v8, 7 bitop3:0x6c
	v_lshlrev_b32_e32 v182, 4, v7
	v_or_b32_e32 v7, 2, v8
	v_bitop3_b32 v7, v6, v7, 7 bitop3:0x6c
	v_lshlrev_b32_e32 v183, 4, v7
	v_or_b32_e32 v7, 4, v8
	v_lshrrev_b32_e32 v9, 4, v2
	v_bitop3_b32 v7, v6, v7, 7 bitop3:0x6c
	v_ashrrev_i32_e32 v160, 3, v2
	v_bfe_u32 v5, v2, 1, 3
	v_xor_b32_e32 v2, v9, v2
	v_lshlrev_b32_e32 v184, 4, v7
	v_or_b32_e32 v7, 6, v8
	v_bitop3_b32 v3, v8, v3, 7 bitop3:0x78
	v_lshlrev_b32_e32 v2, 3, v2
	v_bitop3_b32 v6, v6, v7, 7 bitop3:0x6c
	v_lshlrev_b32_e32 v187, 4, v3
	v_bitop3_b32 v3, v8, v5, 2 bitop3:0x36
	v_lshlrev_b32_e32 v0, 3, v8
	v_and_b32_e32 v2, 56, v2
	v_lshlrev_b32_e32 v4, 2, v8
	v_lshlrev_b32_e32 v192, 4, v8
	v_lshlrev_b32_e32 v185, 4, v6
	v_bitop3_b32 v6, v8, v5, 4 bitop3:0x36
	v_lshlrev_b32_e32 v188, 4, v3
	v_bitop3_b32 v3, v8, v5, 6 bitop3:0x36
	v_ashrrev_i32_e32 v161, 31, v160
	v_lshl_add_u64 v[162:163], s[26:27], 0, v[192:193]
	s_add_i32 s26, s5, 0x10000
	s_add_i32 s27, s5, 0x12000
	s_add_i32 s34, s5, 0x14000
	s_add_i32 s35, s5, 0x16000
	s_add_i32 s36, s5, 0x18000
	s_add_i32 s37, s5, 0x1a000
	s_add_i32 s44, s5, 0x1c000
	s_add_i32 s45, s5, 0x1e000
	v_lshlrev_b32_e32 v186, 4, v6
	v_lshlrev_b32_e32 v189, 4, v3
	v_add_u32_e32 v190, 0, v1
	s_mov_b32 s46, 0
	v_lshlrev_b32_e32 v192, 1, v0
	v_lshlrev_b32_e32 v164, 1, v2
	v_lshlrev_b32_e32 v166, 1, v4
	v_add_u32_e32 v182, v179, v182
	v_add_u32_e32 v183, v179, v183
	v_add_u32_e32 v184, v179, v184
	v_add_u32_e32 v185, v179, v185
	v_add_u32_e32 v187, v190, v187
	v_add_u32_e32 v188, v190, v188
	v_add_u32_e32 v186, v190, v186
	v_add_u32_e32 v189, v190, v189
	v_add_u32_e32 v187, 0x10000, v187
	v_add_u32_e32 v188, 0x10000, v188
	v_add_u32_e32 v186, 0x10000, v186
	v_add_u32_e32 v189, 0x10000, v189
	s_add_u32 s26, s6, 0x800
	s_addc_u32 s27, s7, 0
	s_mov_b32 s35, 0
	s_mov_b32 s2, s0
	s_branch .LBB0_629

.LBB0_629:
	s_lshl_b32 s30, s46, 4
	s_add_i32 s38, s1, s30
	v_readlane_b32 s30, v253, 52
	s_ashr_i32 s39, s2, 4
	v_readlane_b32 s31, v253, 53
	s_and_b64 s[30:31], s[30:31], exec
	s_cselect_b32 s39, s38, s39
	s_cselect_b32 s2, s4, s2
	s_ashr_i32 s40, s39, 3
	s_and_b32 s38, s2, 15
	s_ashr_i32 s41, s40, 31
	s_lshl_b64 s[42:43], s[40:41], 11
	v_lshl_or_b32 v0, s38, 7, v178
	v_or_b32_e32 v168, s42, v0
	v_mov_b64_e32 v[0:1], s[6:7]
	s_movk_i32 s47, 0x1100
	s_lshl_b32 s2, s39, 7
	v_mad_u64_u32 v[2:3], s[30:31], v168, s47, v[0:1]
	s_and_b32 s2, s2, 0x380
	v_mad_i32_i24 v3, s43, v242, v3
	s_lshl_b32 s30, s2, 1
	s_mov_b32 s31, s3
	v_lshl_add_u64 v[2:3], v[2:3], 0, s[30:31]
	v_lshl_add_u64 v[2:3], s[14:15], 1, v[2:3]
	v_lshl_add_u64 v[2:3], v[2:3], 0, v[192:193]
	s_cmp_lg_u32 s35, 0
	s_cbranch_scc1 .Lattn_skipq
	global_load_dwordx4 v[128:131], v[2:3], off
	global_load_dwordx4 v[132:135], v[2:3], off offset:32
	global_load_dwordx4 v[136:139], v[2:3], off offset:64
	global_load_dwordx4 v[140:143], v[2:3], off offset:96
.Lattn_skipq:
	v_lshl_add_u64 v[2:3], s[42:43], 0, v[160:161]
	v_mov_b32_e32 v169, s43
	v_mad_u64_u32 v[0:1], s[42:43], v2, s47, v[0:1]
	v_mad_i32_i24 v1, v3, s47, v1
	v_lshl_add_u64 v[0:1], v[0:1], 0, s[30:31]
	v_mov_b32_e32 v165, v193
	v_lshl_add_u64 v[170:171], v[0:1], 0, v[164:165]
	v_add_u32_e32 v2, s2, v160
	v_mov_b64_e32 v[0:1], s[10:11]
	v_mad_i64_i32 v[0:1], s[42:43], v2, s73, v[0:1]
	s_lshl_b64 s[40:41], s[40:41], 12
	v_lshl_add_u64 v[0:1], v[0:1], 0, s[40:41]
	s_mul_i32 s2, s38, 0x88000
	v_lshl_add_u64 v[172:173], v[0:1], 0, v[164:165]
	s_lshl_b32 s31, s38, 1
	s_not_b64 s[38:39], s[16:17]
	v_and_b32_e32 v34, 64, v240
	v_xor_b32_e32 v33, 32, v240
	v_add_u32_e32 v34, 64, v34
	v_cmp_lt_i32_e32 vcc, v33, v34
	s_nop 1
	v_cndmask_b32_e32 v33, v240, v33, vcc
	v_lshlrev_b32_e32 v165, 2, v33
	s_mov_b32 s42, s31
	v_subrev_u32_e32 v170, s6, v170
	v_subrev_u32_e32 v172, s10, v172
	s_cmp_lg_u32 s35, 0
	s_cbranch_scc0 .Lattn_pro_np
	s_add_i32 s2, s42, 2
	s_and_b32 s2, s2, 31
	s_mul_i32 s2, s2, 0x44000
	s_add_i32 m0, s5, 32768
	s_add_u32 s40, s26, s2
	s_addc_u32 s41, s27, 0
	global_load_lds_dwordx4 v170, s[40:41]
	s_add_i32 m0, s5, 40960
	s_add_u32 s40, s40, 0x80
	s_addc_u32 s41, s41, 0
	global_load_lds_dwordx4 v170, s[40:41]
	s_add_i32 s2, s42, 1
	s_and_b32 s2, s2, 31
	s_lshl_b32 s2, s2, 7
	s_add_i32 m0, s5, 81920
	s_add_u32 s44, s10, s2
	s_addc_u32 s45, s11, 0
	global_load_lds_dwordx4 v172, s[44:45]
	s_add_i32 m0, s5, 90112
	s_add_u32 s44, s44, 0x204000
	s_addc_u32 s45, s45, 0
	global_load_lds_dwordx4 v172, s[44:45]
	v_mov_b32_e32 v128, v144
	v_mov_b32_e32 v129, v145
	v_mov_b32_e32 v130, v146
	v_mov_b32_e32 v131, v147
	v_mov_b32_e32 v132, v148
	v_mov_b32_e32 v133, v149
	v_mov_b32_e32 v134, v150
	v_mov_b32_e32 v135, v151
	v_mov_b32_e32 v0, 0
	v_mov_b32_e32 v1, 0
	v_mov_b32_e32 v2, 0
	v_mov_b32_e32 v3, 0
	v_mov_b32_e32 v4, 0
	v_mov_b32_e32 v5, 0
	v_mov_b32_e32 v6, 0
	v_mov_b32_e32 v7, 0
	v_mov_b32_e32 v8, 0
	v_mov_b32_e32 v9, 0
	v_mov_b32_e32 v10, 0
	v_mov_b32_e32 v11, 0
	v_mov_b32_e32 v12, 0
	v_mov_b32_e32 v13, 0
	v_mov_b32_e32 v14, 0
	v_mov_b32_e32 v15, 0
	v_mov_b32_e32 v16, 0
	v_mov_b32_e32 v17, 0
	v_mov_b32_e32 v18, 0
	v_mov_b32_e32 v19, 0
	v_mov_b32_e32 v20, 0
	v_mov_b32_e32 v21, 0
	v_mov_b32_e32 v22, 0
	v_mov_b32_e32 v23, 0
	v_mov_b32_e32 v24, 0
	v_mov_b32_e32 v25, 0
	v_mov_b32_e32 v26, 0
	v_mov_b32_e32 v27, 0
	v_mov_b32_e32 v28, 0
	v_mov_b32_e32 v29, 0
	v_mov_b32_e32 v30, 0
	v_mov_b32_e32 v31, 0
	v_mov_b32_e32 v32, 0
	v_mov_b32_e32 v33, 0
	v_mov_b32_e32 v34, 0
	v_mov_b32_e32 v35, 0
	v_mov_b32_e32 v36, 0
	v_mov_b32_e32 v37, 0
	v_mov_b32_e32 v38, 0
	v_mov_b32_e32 v39, 0
	v_mov_b32_e32 v40, 0
	v_mov_b32_e32 v41, 0
	v_mov_b32_e32 v42, 0
	v_mov_b32_e32 v43, 0
	v_mov_b32_e32 v44, 0
	v_mov_b32_e32 v45, 0
	v_mov_b32_e32 v46, 0
	v_mov_b32_e32 v47, 0
	v_mov_b32_e32 v48, 0
	v_mov_b32_e32 v49, 0
	v_mov_b32_e32 v50, 0
	v_mov_b32_e32 v51, 0
	v_mov_b32_e32 v52, 0
	v_mov_b32_e32 v53, 0
	v_mov_b32_e32 v54, 0
	v_mov_b32_e32 v55, 0
	v_mov_b32_e32 v56, 0
	v_mov_b32_e32 v57, 0
	v_mov_b32_e32 v58, 0
	v_mov_b32_e32 v59, 0
	v_mov_b32_e32 v60, 0
	v_mov_b32_e32 v61, 0
	v_mov_b32_e32 v62, 0
	v_mov_b32_e32 v63, 0
	v_mov_b32_e32 v167, 0
	v_mov_b32_e32 v175, 0
	v_mov_b32_e32 v174, 1.0
	s_waitcnt vmcnt(4)
	s_branch .Lattn_pro_join
.Lattn_pro_np:
	s_add_i32 s2, s42, 0
	s_and_b32 s2, s2, 31
	s_mul_i32 s2, s2, 0x44000
	s_add_i32 m0, s5, 0
	s_add_u32 s40, s26, s2
	s_addc_u32 s41, s27, 0
	global_load_lds_dwordx4 v170, s[40:41]
	s_add_i32 m0, s5, 8192
	s_add_u32 s40, s40, 0x80
	s_addc_u32 s41, s41, 0
	global_load_lds_dwordx4 v170, s[40:41]
	s_add_i32 s2, s42, 1
	s_and_b32 s2, s2, 31
	s_mul_i32 s2, s2, 0x44000
	s_add_i32 m0, s5, 16384
	s_add_u32 s40, s26, s2
	s_addc_u32 s41, s27, 0
	global_load_lds_dwordx4 v170, s[40:41]
	s_add_i32 m0, s5, 24576
	s_add_u32 s40, s40, 0x80
	s_addc_u32 s41, s41, 0
	global_load_lds_dwordx4 v170, s[40:41]
	s_add_i32 s2, s42, 0
	s_and_b32 s2, s2, 31
	s_lshl_b32 s2, s2, 7
	s_add_i32 m0, s5, 65536
	s_add_u32 s44, s10, s2
	s_addc_u32 s45, s11, 0
	global_load_lds_dwordx4 v172, s[44:45]
	s_add_i32 m0, s5, 73728
	s_add_u32 s44, s44, 0x204000
	s_addc_u32 s45, s45, 0
	global_load_lds_dwordx4 v172, s[44:45]
	s_add_i32 s2, s42, 2
	s_and_b32 s2, s2, 31
	s_mul_i32 s2, s2, 0x44000
	s_add_i32 m0, s5, 32768
	s_add_u32 s40, s26, s2
	s_addc_u32 s41, s27, 0
	global_load_lds_dwordx4 v170, s[40:41]
	s_add_i32 m0, s5, 40960
	s_add_u32 s40, s40, 0x80
	s_addc_u32 s41, s41, 0
	global_load_lds_dwordx4 v170, s[40:41]
	s_add_i32 s2, s42, 1
	s_and_b32 s2, s2, 31
	s_lshl_b32 s2, s2, 7
	s_add_i32 m0, s5, 81920
	s_add_u32 s44, s10, s2
	s_addc_u32 s45, s11, 0
	global_load_lds_dwordx4 v172, s[44:45]
	s_add_i32 m0, s5, 90112
	s_add_u32 s44, s44, 0x204000
	s_addc_u32 s45, s45, 0
	global_load_lds_dwordx4 v172, s[44:45]
	v_mov_b32_e32 v0, 0
	v_mov_b32_e32 v1, 0
	v_mov_b32_e32 v2, 0
	v_mov_b32_e32 v3, 0
	v_mov_b32_e32 v4, 0
	v_mov_b32_e32 v5, 0
	v_mov_b32_e32 v6, 0
	v_mov_b32_e32 v7, 0
	v_mov_b32_e32 v8, 0
	v_mov_b32_e32 v9, 0
	v_mov_b32_e32 v10, 0
	v_mov_b32_e32 v11, 0
	v_mov_b32_e32 v12, 0
	v_mov_b32_e32 v13, 0
	v_mov_b32_e32 v14, 0
	v_mov_b32_e32 v15, 0
	v_mov_b32_e32 v16, 0
	v_mov_b32_e32 v17, 0
	v_mov_b32_e32 v18, 0
	v_mov_b32_e32 v19, 0
	v_mov_b32_e32 v20, 0
	v_mov_b32_e32 v21, 0
	v_mov_b32_e32 v22, 0
	v_mov_b32_e32 v23, 0
	v_mov_b32_e32 v24, 0
	v_mov_b32_e32 v25, 0
	v_mov_b32_e32 v26, 0
	v_mov_b32_e32 v27, 0
	v_mov_b32_e32 v28, 0
	v_mov_b32_e32 v29, 0
	v_mov_b32_e32 v30, 0
	v_mov_b32_e32 v31, 0
	v_mov_b32_e32 v32, 0
	v_mov_b32_e32 v33, 0
	v_mov_b32_e32 v34, 0
	v_mov_b32_e32 v35, 0
	v_mov_b32_e32 v36, 0
	v_mov_b32_e32 v37, 0
	v_mov_b32_e32 v38, 0
	v_mov_b32_e32 v39, 0
	v_mov_b32_e32 v40, 0
	v_mov_b32_e32 v41, 0
	v_mov_b32_e32 v42, 0
	v_mov_b32_e32 v43, 0
	v_mov_b32_e32 v44, 0
	v_mov_b32_e32 v45, 0
	v_mov_b32_e32 v46, 0
	v_mov_b32_e32 v47, 0
	v_mov_b32_e32 v48, 0
	v_mov_b32_e32 v49, 0
	v_mov_b32_e32 v50, 0
	v_mov_b32_e32 v51, 0
	v_mov_b32_e32 v52, 0
	v_mov_b32_e32 v53, 0
	v_mov_b32_e32 v54, 0
	v_mov_b32_e32 v55, 0
	v_mov_b32_e32 v56, 0
	v_mov_b32_e32 v57, 0
	v_mov_b32_e32 v58, 0
	v_mov_b32_e32 v59, 0
	v_mov_b32_e32 v60, 0
	v_mov_b32_e32 v61, 0
	v_mov_b32_e32 v62, 0
	v_mov_b32_e32 v63, 0
	v_mov_b32_e32 v167, 0
	v_mov_b32_e32 v175, 0
	v_mov_b32_e32 v174, 1.0
	s_waitcnt vmcnt(8)
.Lattn_pro_join:
	s_barrier
	ds_read_b128 v[96:99], v182 offset:0
	ds_read_b128 v[100:103], v182 offset:4096
	ds_read_b128 v[104:107], v183 offset:0
	ds_read_b128 v[108:111], v183 offset:4096
	ds_read_b128 v[112:115], v184 offset:0
	ds_read_b128 v[116:119], v184 offset:4096
	ds_read_b128 v[120:123], v185 offset:0
	ds_read_b128 v[124:127], v185 offset:4096
	s_waitcnt lgkmcnt(0)
	v_mfma_f32_32x32x16_bf16 v[64:79], v[96:99], v[128:131], 0
	v_mfma_f32_32x32x16_bf16 v[80:95], v[100:103], v[128:131], 0
	v_mfma_f32_32x32x16_bf16 v[64:79], v[104:107], v[132:135], v[64:79]
	v_mfma_f32_32x32x16_bf16 v[80:95], v[108:111], v[132:135], v[80:95]
	v_mfma_f32_32x32x16_bf16 v[64:79], v[112:115], v[136:139], v[64:79]
	v_mfma_f32_32x32x16_bf16 v[80:95], v[116:119], v[136:139], v[80:95]
	v_mfma_f32_32x32x16_bf16 v[64:79], v[120:123], v[140:143], v[64:79]
	v_mfma_f32_32x32x16_bf16 v[80:95], v[124:127], v[140:143], v[80:95]
	s_waitcnt vmcnt(4)
	s_barrier
	ds_read_b128 v[208:211], v182 offset:16384
	ds_read_b128 v[212:215], v182 offset:20480
	ds_read_b128 v[216:219], v183 offset:16384
	ds_read_b128 v[220:223], v183 offset:20480
	ds_read_b128 v[224:227], v184 offset:16384
	ds_read_b128 v[228:231], v184 offset:20480
	s_nop 7
	s_waitcnt lgkmcnt(5)
	v_mfma_f32_32x32x16_bf16 v[96:111], v[208:211], v[128:131], 0
	ds_read_b128 v[208:211], v185 offset:16384
	s_add_i32 s2, s42, 3
	v_max3_f32 v254, v64, v65, v66
	s_and_b32 s2, s2, 31
	v_max3_f32 v255, v80, v81, v82
	s_mul_i32 s2, s2, 0x44000
	v_max3_f32 v254, v254, v67, v68
	s_add_i32 m0, s5, 49152
	v_max3_f32 v255, v255, v83, v84
	s_waitcnt lgkmcnt(5)
	v_mfma_f32_32x32x16_bf16 v[112:127], v[212:215], v[128:131], 0
	ds_read_b128 v[212:215], v185 offset:20480
	s_add_u32 s40, s26, s2
	v_max3_f32 v254, v254, v69, v70
	s_addc_u32 s41, s27, 0
	v_max3_f32 v255, v255, v85, v86
	global_load_lds_dwordx4 v170, s[40:41]
	v_max3_f32 v254, v254, v71, v72
	s_add_i32 m0, s5, 57344
	v_max3_f32 v255, v255, v87, v88
	s_waitcnt lgkmcnt(5)
	v_mfma_f32_32x32x16_bf16 v[96:111], v[216:219], v[132:135], v[96:111]
	ds_read_b128 v[216:219], v187 offset:0
	s_add_u32 s40, s40, 0x80
	v_max3_f32 v254, v254, v73, v74
	s_addc_u32 s41, s41, 0
	v_max3_f32 v255, v255, v89, v90
	global_load_lds_dwordx4 v170, s[40:41]
	v_max3_f32 v254, v254, v75, v76
	s_add_i32 s2, s42, 2
	v_max3_f32 v255, v255, v91, v92
	s_waitcnt lgkmcnt(5)
	v_mfma_f32_32x32x16_bf16 v[112:127], v[220:223], v[132:135], v[112:127]
	ds_read_b128 v[220:223], v187 offset:4096
	s_and_b32 s2, s2, 31
	v_max3_f32 v254, v254, v77, v78
	s_lshl_b32 s2, s2, 7
	v_max3_f32 v255, v255, v93, v94
	s_add_i32 m0, s5, 98304
	v_max3_f32 v254, v254, v79, v95
	s_add_u32 s44, s10, s2
	v_max_f32_e32 v254, v254, v255
	s_waitcnt lgkmcnt(5)
	v_mfma_f32_32x32x16_bf16 v[96:111], v[224:227], v[136:139], v[96:111]
	ds_read_b128 v[224:227], v187 offset:8192
	v_mov_b32_e32 v180, 0xc2800000
	v_cmp_lt_f32_e32 vcc, 0x4138aa3b, v254
	v_cmp_gt_f32_e64 s[40:41], v180, v254
	s_addc_u32 s45, s11, 0
	global_load_lds_dwordx4 v172, s[44:45]
	s_add_i32 m0, s5, 106496
	s_add_u32 s44, s44, 0x204000
	s_addc_u32 s45, s45, 0
	s_waitcnt lgkmcnt(5)
	v_mfma_f32_32x32x16_bf16 v[112:127], v[228:231], v[136:139], v[112:127]
	ds_read_b128 v[228:231], v187 offset:12288
	global_load_lds_dwordx4 v172, s[44:45]
	s_or_b64 vcc, vcc, s[40:41]
	s_nop 0
	s_cbranch_vccnz .Lattn_sp_t0
	v_exp_f32_e32 v64, v64
	v_exp_f32_e32 v65, v65
	v_exp_f32_e32 v66, v66
	v_exp_f32_e32 v67, v67
	v_exp_f32_e32 v68, v68
	v_exp_f32_e32 v69, v69
	v_exp_f32_e32 v70, v70
	v_exp_f32_e32 v71, v71
	v_add_f32_e32 v190, v64, v65
	v_add_f32_e32 v191, v66, v67
	v_add_f32_e32 v190, v190, v68
	v_add_f32_e32 v191, v191, v69
	v_add_f32_e32 v190, v190, v70
	v_add_f32_e32 v191, v191, v71
	v_cvt_pk_bf16_f32 v144, v64, v65
	v_cvt_pk_bf16_f32 v145, v66, v67
	v_cvt_pk_bf16_f32 v146, v68, v69
	v_cvt_pk_bf16_f32 v147, v70, v71
	s_waitcnt lgkmcnt(5)
	v_mfma_f32_32x32x16_bf16 v[96:111], v[208:211], v[140:143], v[96:111]
	ds_read_b128 v[208:211], v188 offset:0
	s_waitcnt lgkmcnt(5)
	v_mfma_f32_32x32x16_bf16 v[112:127], v[212:215], v[140:143], v[112:127]
	ds_read_b128 v[212:215], v188 offset:4096
	v_exp_f32_e32 v72, v72
	v_exp_f32_e32 v73, v73
	v_exp_f32_e32 v74, v74
	v_exp_f32_e32 v75, v75
	v_exp_f32_e32 v76, v76
	v_exp_f32_e32 v77, v77
	v_exp_f32_e32 v78, v78
	v_exp_f32_e32 v79, v79
	v_add_f32_e32 v190, v190, v72
	v_add_f32_e32 v191, v191, v73
	v_add_f32_e32 v190, v190, v74
	v_add_f32_e32 v191, v191, v75
	v_add_f32_e32 v190, v190, v76
	v_add_f32_e32 v191, v191, v77
	v_add_f32_e32 v190, v190, v78
	v_add_f32_e32 v191, v191, v79
	v_cvt_pk_bf16_f32 v148, v72, v73
	v_cvt_pk_bf16_f32 v149, v74, v75
	v_cvt_pk_bf16_f32 v150, v76, v77
	v_cvt_pk_bf16_f32 v151, v78, v79
	v_exp_f32_e32 v80, v80
	v_exp_f32_e32 v81, v81
	v_exp_f32_e32 v82, v82
	v_exp_f32_e32 v83, v83
	v_exp_f32_e32 v84, v84
	v_exp_f32_e32 v85, v85
	v_exp_f32_e32 v86, v86
	v_exp_f32_e32 v87, v87
	v_add_f32_e32 v190, v190, v80
	v_add_f32_e32 v191, v191, v81
	v_add_f32_e32 v190, v190, v82
	v_add_f32_e32 v191, v191, v83
	v_add_f32_e32 v190, v190, v84
	v_add_f32_e32 v191, v191, v85
	v_add_f32_e32 v190, v190, v86
	v_add_f32_e32 v191, v191, v87
	v_cvt_pk_bf16_f32 v152, v80, v81
	v_cvt_pk_bf16_f32 v153, v82, v83
	v_cvt_pk_bf16_f32 v154, v84, v85
	v_cvt_pk_bf16_f32 v155, v86, v87
	v_exp_f32_e32 v88, v88
	v_exp_f32_e32 v89, v89
	v_exp_f32_e32 v90, v90
	v_exp_f32_e32 v91, v91
	v_exp_f32_e32 v92, v92
	v_exp_f32_e32 v93, v93
	v_exp_f32_e32 v94, v94
	v_exp_f32_e32 v95, v95
	v_add_f32_e32 v190, v190, v88
	v_add_f32_e32 v191, v191, v89
	v_add_f32_e32 v190, v190, v90
	v_add_f32_e32 v191, v191, v91
	v_add_f32_e32 v190, v190, v92
	v_add_f32_e32 v191, v191, v93
	v_add_f32_e32 v190, v190, v94
	v_add_f32_e32 v191, v191, v95
	v_cvt_pk_bf16_f32 v156, v88, v89
	v_cvt_pk_bf16_f32 v157, v90, v91
	v_cvt_pk_bf16_f32 v158, v92, v93
	v_cvt_pk_bf16_f32 v159, v94, v95
	v_add_f32_e32 v190, v190, v191
	v_add_f32_e32 v167, v167, v190
	s_add_i32 s42, s31, 1
	s_movk_i32 s47, 7
.Lattn_loop_f:
	s_waitcnt vmcnt(4)
	s_barrier
	s_waitcnt lgkmcnt(5)
	v_mfma_f32_32x32x16_bf16 v[48:63], v[216:219], v[144:147], v[48:63]
	ds_read_b128 v[216:219], v188 offset:8192
	s_add_i32 s2, s42, 3
	s_and_b32 s2, s2, 31
	s_mul_i32 s2, s2, 0x44000
	s_add_i32 m0, s5, 0
	s_add_u32 s40, s26, s2
	s_addc_u32 s41, s27, 0
	global_load_lds_dwordx4 v170, s[40:41]
	s_add_i32 m0, s5, 8192
	s_waitcnt lgkmcnt(5)
	v_mfma_f32_32x32x16_bf16 v[32:47], v[220:223], v[144:147], v[32:47]
	ds_read_b128 v[220:223], v188 offset:12288
	s_add_u32 s40, s40, 0x80
	s_addc_u32 s41, s41, 0
	global_load_lds_dwordx4 v170, s[40:41]
	s_add_i32 s2, s42, 2
	s_and_b32 s2, s2, 31
	s_lshl_b32 s2, s2, 7
	s_add_i32 m0, s5, 114688
	s_add_u32 s44, s10, s2
	s_waitcnt lgkmcnt(5)
	v_mfma_f32_32x32x16_bf16 v[16:31], v[224:227], v[144:147], v[16:31]
	ds_read_b128 v[224:227], v186 offset:0
	s_addc_u32 s45, s11, 0
	global_load_lds_dwordx4 v172, s[44:45]
	s_add_i32 m0, s5, 122880
	s_add_u32 s44, s44, 0x204000
	s_addc_u32 s45, s45, 0
	global_load_lds_dwordx4 v172, s[44:45]
	s_waitcnt lgkmcnt(5)
	v_mfma_f32_32x32x16_bf16 v[0:15], v[228:231], v[144:147], v[0:15]
	ds_read_b128 v[228:231], v186 offset:4096
	v_exp_f32_e32 v171, v96
	v_exp_f32_e32 v173, v97
	v_exp_f32_e32 v179, v98
	v_exp_f32_e32 v180, v99
	s_waitcnt lgkmcnt(5)
	v_mfma_f32_32x32x16_bf16 v[48:63], v[208:211], v[148:151], v[48:63]
	ds_read_b128 v[208:211], v186 offset:8192
	v_exp_f32_e32 v232, v100
	v_exp_f32_e32 v233, v101
	v_exp_f32_e32 v234, v102
	v_exp_f32_e32 v235, v103
	s_waitcnt lgkmcnt(5)
	v_mfma_f32_32x32x16_bf16 v[32:47], v[212:215], v[148:151], v[32:47]
	ds_read_b128 v[212:215], v186 offset:12288
	v_add_f32_e32 v190, v171, v173
	v_add_f32_e32 v191, v179, v180
	v_add_f32_e32 v190, v190, v232
	v_add_f32_e32 v191, v191, v233
	s_waitcnt lgkmcnt(5)
	v_mfma_f32_32x32x16_bf16 v[16:31], v[216:219], v[148:151], v[16:31]
	ds_read_b128 v[216:219], v189 offset:0
	v_add_f32_e32 v190, v190, v234
	v_add_f32_e32 v191, v191, v235
	v_cvt_pk_bf16_f32 v144, v171, v173
	v_cvt_pk_bf16_f32 v145, v179, v180
	s_waitcnt lgkmcnt(5)
	v_mfma_f32_32x32x16_bf16 v[0:15], v[220:223], v[148:151], v[0:15]
	ds_read_b128 v[220:223], v189 offset:4096
	v_cvt_pk_bf16_f32 v146, v232, v233
	v_cvt_pk_bf16_f32 v147, v234, v235
	v_exp_f32_e32 v171, v104
	v_exp_f32_e32 v173, v105
	s_waitcnt lgkmcnt(5)
	v_mfma_f32_32x32x16_bf16 v[48:63], v[224:227], v[152:155], v[48:63]
	ds_read_b128 v[224:227], v189 offset:8192
	v_exp_f32_e32 v179, v106
	v_exp_f32_e32 v180, v107
	v_exp_f32_e32 v232, v108
	v_exp_f32_e32 v233, v109
	s_waitcnt lgkmcnt(5)
	v_mfma_f32_32x32x16_bf16 v[32:47], v[228:231], v[152:155], v[32:47]
	ds_read_b128 v[228:231], v189 offset:12288
	v_exp_f32_e32 v234, v110
	v_exp_f32_e32 v235, v111
	v_add_f32_e32 v190, v190, v171
	v_add_f32_e32 v191, v191, v173
	s_waitcnt lgkmcnt(5)
	v_mfma_f32_32x32x16_bf16 v[16:31], v[208:211], v[152:155], v[16:31]
	ds_read_b128 v[208:211], v182 offset:32768
	v_add_f32_e32 v190, v190, v179
	v_add_f32_e32 v191, v191, v180
	v_add_f32_e32 v190, v190, v232
	v_add_f32_e32 v191, v191, v233
	s_waitcnt lgkmcnt(5)
	v_mfma_f32_32x32x16_bf16 v[0:15], v[212:215], v[152:155], v[0:15]
	ds_read_b128 v[212:215], v182 offset:36864
	v_add_f32_e32 v190, v190, v234
	v_add_f32_e32 v191, v191, v235
	v_cvt_pk_bf16_f32 v148, v171, v173
	v_cvt_pk_bf16_f32 v149, v179, v180
	s_waitcnt lgkmcnt(5)
	v_mfma_f32_32x32x16_bf16 v[48:63], v[216:219], v[156:159], v[48:63]
	ds_read_b128 v[216:219], v183 offset:32768
	v_cvt_pk_bf16_f32 v150, v232, v233
	v_cvt_pk_bf16_f32 v151, v234, v235
	v_exp_f32_e32 v171, v112
	v_exp_f32_e32 v173, v113
	s_waitcnt lgkmcnt(5)
	v_mfma_f32_32x32x16_bf16 v[32:47], v[220:223], v[156:159], v[32:47]
	ds_read_b128 v[220:223], v183 offset:36864
	v_exp_f32_e32 v179, v114
	v_exp_f32_e32 v180, v115
	v_exp_f32_e32 v232, v116
	v_exp_f32_e32 v233, v117
	s_waitcnt lgkmcnt(5)
	v_mfma_f32_32x32x16_bf16 v[16:31], v[224:227], v[156:159], v[16:31]
	ds_read_b128 v[224:227], v184 offset:32768
	v_exp_f32_e32 v234, v118
	v_exp_f32_e32 v235, v119
	v_add_f32_e32 v190, v190, v171
	v_add_f32_e32 v191, v191, v173
	s_waitcnt lgkmcnt(5)
	v_mfma_f32_32x32x16_bf16 v[0:15], v[228:231], v[156:159], v[0:15]
	ds_read_b128 v[228:231], v184 offset:36864
	v_add_f32_e32 v190, v190, v179
	v_add_f32_e32 v191, v191, v180
	v_add_f32_e32 v190, v190, v232
	v_add_f32_e32 v191, v191, v233
	s_waitcnt lgkmcnt(5)
	v_mfma_f32_32x32x16_bf16 v[64:79], v[208:211], v[128:131], 0
	ds_read_b128 v[208:211], v185 offset:32768
	v_add_f32_e32 v190, v190, v234
	v_add_f32_e32 v191, v191, v235
	v_cvt_pk_bf16_f32 v152, v171, v173
	v_cvt_pk_bf16_f32 v153, v179, v180
	s_waitcnt lgkmcnt(5)
	v_mfma_f32_32x32x16_bf16 v[80:95], v[212:215], v[128:131], 0
	ds_read_b128 v[212:215], v185 offset:36864
	v_cvt_pk_bf16_f32 v154, v232, v233
	v_cvt_pk_bf16_f32 v155, v234, v235
	v_exp_f32_e32 v171, v120
	v_exp_f32_e32 v173, v121
	s_waitcnt lgkmcnt(5)
	v_mfma_f32_32x32x16_bf16 v[64:79], v[216:219], v[132:135], v[64:79]
	ds_read_b128 v[216:219], v187 offset:16384
	v_exp_f32_e32 v179, v122
	v_exp_f32_e32 v180, v123
	v_exp_f32_e32 v232, v124
	v_exp_f32_e32 v233, v125
	s_waitcnt lgkmcnt(5)
	v_mfma_f32_32x32x16_bf16 v[80:95], v[220:223], v[132:135], v[80:95]
	ds_read_b128 v[220:223], v187 offset:20480
	v_exp_f32_e32 v234, v126
	v_exp_f32_e32 v235, v127
	v_add_f32_e32 v190, v190, v171
	s_waitcnt lgkmcnt(5)
	v_mfma_f32_32x32x16_bf16 v[64:79], v[224:227], v[136:139], v[64:79]
	ds_read_b128 v[224:227], v187 offset:24576
	v_add_f32_e32 v191, v191, v173
	v_add_f32_e32 v190, v190, v179
	v_add_f32_e32 v191, v191, v180
	s_waitcnt lgkmcnt(5)
	v_mfma_f32_32x32x16_bf16 v[80:95], v[228:231], v[136:139], v[80:95]
	ds_read_b128 v[228:231], v187 offset:28672
	v_add_f32_e32 v190, v190, v232
	v_add_f32_e32 v191, v191, v233
	v_add_f32_e32 v190, v190, v234
	s_waitcnt lgkmcnt(5)
	v_mfma_f32_32x32x16_bf16 v[64:79], v[208:211], v[140:143], v[64:79]
	ds_read_b128 v[208:211], v188 offset:16384
	v_add_f32_e32 v191, v191, v235
	v_cvt_pk_bf16_f32 v156, v171, v173
	v_cvt_pk_bf16_f32 v157, v179, v180
	s_waitcnt lgkmcnt(5)
	v_mfma_f32_32x32x16_bf16 v[80:95], v[212:215], v[140:143], v[80:95]
	ds_read_b128 v[212:215], v188 offset:20480
	v_cvt_pk_bf16_f32 v158, v232, v233
	v_cvt_pk_bf16_f32 v159, v234, v235
	v_add_f32_e32 v190, v190, v191
	v_cmp_ngt_f32_e32 vcc, 0x71800000, v190
	s_nop 4
	s_cbranch_vccnz .Lattn_redo_L0
	v_add_f32_e32 v167, v167, v190
	s_waitcnt vmcnt(4)
	s_barrier
	s_waitcnt lgkmcnt(5)
	v_mfma_f32_32x32x16_bf16 v[48:63], v[216:219], v[144:147], v[48:63]
	ds_read_b128 v[216:219], v188 offset:24576
	s_add_i32 s2, s42, 4
	s_and_b32 s2, s2, 31
	s_mul_i32 s2, s2, 0x44000
	s_add_i32 m0, s5, 16384
	s_add_u32 s40, s26, s2
	s_addc_u32 s41, s27, 0
	global_load_lds_dwordx4 v170, s[40:41]
	s_add_i32 m0, s5, 24576
	s_waitcnt lgkmcnt(5)
	v_mfma_f32_32x32x16_bf16 v[32:47], v[220:223], v[144:147], v[32:47]
	ds_read_b128 v[220:223], v188 offset:28672
	s_add_u32 s40, s40, 0x80
	s_addc_u32 s41, s41, 0
	global_load_lds_dwordx4 v170, s[40:41]
	s_add_i32 s2, s42, 3
	s_and_b32 s2, s2, 31
	s_lshl_b32 s2, s2, 7
	s_add_i32 m0, s5, 65536
	s_add_u32 s44, s10, s2
	s_waitcnt lgkmcnt(5)
	v_mfma_f32_32x32x16_bf16 v[16:31], v[224:227], v[144:147], v[16:31]
	ds_read_b128 v[224:227], v186 offset:16384
	s_addc_u32 s45, s11, 0
	global_load_lds_dwordx4 v172, s[44:45]
	s_add_i32 m0, s5, 73728
	s_add_u32 s44, s44, 0x204000
	s_addc_u32 s45, s45, 0
	global_load_lds_dwordx4 v172, s[44:45]
	s_waitcnt lgkmcnt(5)
	v_mfma_f32_32x32x16_bf16 v[0:15], v[228:231], v[144:147], v[0:15]
	ds_read_b128 v[228:231], v186 offset:20480
	v_exp_f32_e32 v171, v64
	v_exp_f32_e32 v173, v65
	v_exp_f32_e32 v179, v66
	v_exp_f32_e32 v180, v67
	s_waitcnt lgkmcnt(5)
	v_mfma_f32_32x32x16_bf16 v[48:63], v[208:211], v[148:151], v[48:63]
	ds_read_b128 v[208:211], v186 offset:24576
	v_exp_f32_e32 v232, v68
	v_exp_f32_e32 v233, v69
	v_exp_f32_e32 v234, v70
	v_exp_f32_e32 v235, v71
	s_waitcnt lgkmcnt(5)
	v_mfma_f32_32x32x16_bf16 v[32:47], v[212:215], v[148:151], v[32:47]
	ds_read_b128 v[212:215], v186 offset:28672
	v_add_f32_e32 v190, v171, v173
	v_add_f32_e32 v191, v179, v180
	v_add_f32_e32 v190, v190, v232
	v_add_f32_e32 v191, v191, v233
	s_waitcnt lgkmcnt(5)
	v_mfma_f32_32x32x16_bf16 v[16:31], v[216:219], v[148:151], v[16:31]
	ds_read_b128 v[216:219], v189 offset:16384
	v_add_f32_e32 v190, v190, v234
	v_add_f32_e32 v191, v191, v235
	v_cvt_pk_bf16_f32 v144, v171, v173
	v_cvt_pk_bf16_f32 v145, v179, v180
	s_waitcnt lgkmcnt(5)
	v_mfma_f32_32x32x16_bf16 v[0:15], v[220:223], v[148:151], v[0:15]
	ds_read_b128 v[220:223], v189 offset:20480
	v_cvt_pk_bf16_f32 v146, v232, v233
	v_cvt_pk_bf16_f32 v147, v234, v235
	v_exp_f32_e32 v171, v72
	v_exp_f32_e32 v173, v73
	s_waitcnt lgkmcnt(5)
	v_mfma_f32_32x32x16_bf16 v[48:63], v[224:227], v[152:155], v[48:63]
	ds_read_b128 v[224:227], v189 offset:24576
	v_exp_f32_e32 v179, v74
	v_exp_f32_e32 v180, v75
	v_exp_f32_e32 v232, v76
	v_exp_f32_e32 v233, v77
	s_waitcnt lgkmcnt(5)
	v_mfma_f32_32x32x16_bf16 v[32:47], v[228:231], v[152:155], v[32:47]
	ds_read_b128 v[228:231], v189 offset:28672
	v_exp_f32_e32 v234, v78
	v_exp_f32_e32 v235, v79
	v_add_f32_e32 v190, v190, v171
	v_add_f32_e32 v191, v191, v173
	s_waitcnt lgkmcnt(5)
	v_mfma_f32_32x32x16_bf16 v[16:31], v[208:211], v[152:155], v[16:31]
	ds_read_b128 v[208:211], v182 offset:49152
	v_add_f32_e32 v190, v190, v179
	v_add_f32_e32 v191, v191, v180
	v_add_f32_e32 v190, v190, v232
	v_add_f32_e32 v191, v191, v233
	s_waitcnt lgkmcnt(5)
	v_mfma_f32_32x32x16_bf16 v[0:15], v[212:215], v[152:155], v[0:15]
	ds_read_b128 v[212:215], v182 offset:53248
	v_add_f32_e32 v190, v190, v234
	v_add_f32_e32 v191, v191, v235
	v_cvt_pk_bf16_f32 v148, v171, v173
	v_cvt_pk_bf16_f32 v149, v179, v180
	s_waitcnt lgkmcnt(5)
	v_mfma_f32_32x32x16_bf16 v[48:63], v[216:219], v[156:159], v[48:63]
	ds_read_b128 v[216:219], v183 offset:49152
	v_cvt_pk_bf16_f32 v150, v232, v233
	v_cvt_pk_bf16_f32 v151, v234, v235
	v_exp_f32_e32 v171, v80
	v_exp_f32_e32 v173, v81
	s_waitcnt lgkmcnt(5)
	v_mfma_f32_32x32x16_bf16 v[32:47], v[220:223], v[156:159], v[32:47]
	ds_read_b128 v[220:223], v183 offset:53248
	v_exp_f32_e32 v179, v82
	v_exp_f32_e32 v180, v83
	v_exp_f32_e32 v232, v84
	v_exp_f32_e32 v233, v85
	s_waitcnt lgkmcnt(5)
	v_mfma_f32_32x32x16_bf16 v[16:31], v[224:227], v[156:159], v[16:31]
	ds_read_b128 v[224:227], v184 offset:49152
	v_exp_f32_e32 v234, v86
	v_exp_f32_e32 v235, v87
	v_add_f32_e32 v190, v190, v171
	v_add_f32_e32 v191, v191, v173
	s_waitcnt lgkmcnt(5)
	v_mfma_f32_32x32x16_bf16 v[0:15], v[228:231], v[156:159], v[0:15]
	ds_read_b128 v[228:231], v184 offset:53248
	v_add_f32_e32 v190, v190, v179
	v_add_f32_e32 v191, v191, v180
	v_add_f32_e32 v190, v190, v232
	v_add_f32_e32 v191, v191, v233
	s_waitcnt lgkmcnt(5)
	v_mfma_f32_32x32x16_bf16 v[96:111], v[208:211], v[128:131], 0
	ds_read_b128 v[208:211], v185 offset:49152
	v_add_f32_e32 v190, v190, v234
	v_add_f32_e32 v191, v191, v235
	v_cvt_pk_bf16_f32 v152, v171, v173
	v_cvt_pk_bf16_f32 v153, v179, v180
	s_waitcnt lgkmcnt(5)
	v_mfma_f32_32x32x16_bf16 v[112:127], v[212:215], v[128:131], 0
	ds_read_b128 v[212:215], v185 offset:53248
	v_cvt_pk_bf16_f32 v154, v232, v233
	v_cvt_pk_bf16_f32 v155, v234, v235
	v_exp_f32_e32 v171, v88
	v_exp_f32_e32 v173, v89
	s_waitcnt lgkmcnt(5)
	v_mfma_f32_32x32x16_bf16 v[96:111], v[216:219], v[132:135], v[96:111]
	ds_read_b128 v[216:219], v187 offset:32768
	v_exp_f32_e32 v179, v90
	v_exp_f32_e32 v180, v91
	v_exp_f32_e32 v232, v92
	v_exp_f32_e32 v233, v93
	s_waitcnt lgkmcnt(5)
	v_mfma_f32_32x32x16_bf16 v[112:127], v[220:223], v[132:135], v[112:127]
	ds_read_b128 v[220:223], v187 offset:36864
	v_exp_f32_e32 v234, v94
	v_exp_f32_e32 v235, v95
	v_add_f32_e32 v190, v190, v171
	s_waitcnt lgkmcnt(5)
	v_mfma_f32_32x32x16_bf16 v[96:111], v[224:227], v[136:139], v[96:111]
	ds_read_b128 v[224:227], v187 offset:40960
	v_add_f32_e32 v191, v191, v173
	v_add_f32_e32 v190, v190, v179
	v_add_f32_e32 v191, v191, v180
	s_waitcnt lgkmcnt(5)
	v_mfma_f32_32x32x16_bf16 v[112:127], v[228:231], v[136:139], v[112:127]
	ds_read_b128 v[228:231], v187 offset:45056
	v_add_f32_e32 v190, v190, v232
	v_add_f32_e32 v191, v191, v233
	v_add_f32_e32 v190, v190, v234
	s_waitcnt lgkmcnt(5)
	v_mfma_f32_32x32x16_bf16 v[96:111], v[208:211], v[140:143], v[96:111]
	ds_read_b128 v[208:211], v188 offset:32768
	v_add_f32_e32 v191, v191, v235
	v_cvt_pk_bf16_f32 v156, v171, v173
	v_cvt_pk_bf16_f32 v157, v179, v180
	s_waitcnt lgkmcnt(5)
	v_mfma_f32_32x32x16_bf16 v[112:127], v[212:215], v[140:143], v[112:127]
	ds_read_b128 v[212:215], v188 offset:36864
	v_cvt_pk_bf16_f32 v158, v232, v233
	v_cvt_pk_bf16_f32 v159, v234, v235
	v_add_f32_e32 v190, v190, v191
	v_cmp_ngt_f32_e32 vcc, 0x71800000, v190
	s_nop 4
	s_cbranch_vccnz .Lattn_redo_L1
	v_add_f32_e32 v167, v167, v190
	s_waitcnt vmcnt(4)
	s_barrier
	s_waitcnt lgkmcnt(5)
	v_mfma_f32_32x32x16_bf16 v[48:63], v[216:219], v[144:147], v[48:63]
	ds_read_b128 v[216:219], v188 offset:40960
	s_add_i32 s2, s42, 5
	s_and_b32 s2, s2, 31
	s_mul_i32 s2, s2, 0x44000
	s_add_i32 m0, s5, 32768
	s_add_u32 s40, s26, s2
	s_addc_u32 s41, s27, 0
	global_load_lds_dwordx4 v170, s[40:41]
	s_add_i32 m0, s5, 40960
	s_waitcnt lgkmcnt(5)
	v_mfma_f32_32x32x16_bf16 v[32:47], v[220:223], v[144:147], v[32:47]
	ds_read_b128 v[220:223], v188 offset:45056
	s_add_u32 s40, s40, 0x80
	s_addc_u32 s41, s41, 0
	global_load_lds_dwordx4 v170, s[40:41]
	s_add_i32 s2, s42, 4
	s_and_b32 s2, s2, 31
	s_lshl_b32 s2, s2, 7
	s_add_i32 m0, s5, 81920
	s_add_u32 s44, s10, s2
	s_waitcnt lgkmcnt(5)
	v_mfma_f32_32x32x16_bf16 v[16:31], v[224:227], v[144:147], v[16:31]
	ds_read_b128 v[224:227], v186 offset:32768
	s_addc_u32 s45, s11, 0
	global_load_lds_dwordx4 v172, s[44:45]
	s_add_i32 m0, s5, 90112
	s_add_u32 s44, s44, 0x204000
	s_addc_u32 s45, s45, 0
	global_load_lds_dwordx4 v172, s[44:45]
	s_waitcnt lgkmcnt(5)
	v_mfma_f32_32x32x16_bf16 v[0:15], v[228:231], v[144:147], v[0:15]
	ds_read_b128 v[228:231], v186 offset:36864
	v_exp_f32_e32 v171, v96
	v_exp_f32_e32 v173, v97
	v_exp_f32_e32 v179, v98
	v_exp_f32_e32 v180, v99
	s_waitcnt lgkmcnt(5)
	v_mfma_f32_32x32x16_bf16 v[48:63], v[208:211], v[148:151], v[48:63]
	ds_read_b128 v[208:211], v186 offset:40960
	v_exp_f32_e32 v232, v100
	v_exp_f32_e32 v233, v101
	v_exp_f32_e32 v234, v102
	v_exp_f32_e32 v235, v103
	s_waitcnt lgkmcnt(5)
	v_mfma_f32_32x32x16_bf16 v[32:47], v[212:215], v[148:151], v[32:47]
	ds_read_b128 v[212:215], v186 offset:45056
	v_add_f32_e32 v190, v171, v173
	v_add_f32_e32 v191, v179, v180
	v_add_f32_e32 v190, v190, v232
	v_add_f32_e32 v191, v191, v233
	s_waitcnt lgkmcnt(5)
	v_mfma_f32_32x32x16_bf16 v[16:31], v[216:219], v[148:151], v[16:31]
	ds_read_b128 v[216:219], v189 offset:32768
	v_add_f32_e32 v190, v190, v234
	v_add_f32_e32 v191, v191, v235
	v_cvt_pk_bf16_f32 v144, v171, v173
	v_cvt_pk_bf16_f32 v145, v179, v180
	s_waitcnt lgkmcnt(5)
	v_mfma_f32_32x32x16_bf16 v[0:15], v[220:223], v[148:151], v[0:15]
	ds_read_b128 v[220:223], v189 offset:36864
	v_cvt_pk_bf16_f32 v146, v232, v233
	v_cvt_pk_bf16_f32 v147, v234, v235
	v_exp_f32_e32 v171, v104
	v_exp_f32_e32 v173, v105
	s_waitcnt lgkmcnt(5)
	v_mfma_f32_32x32x16_bf16 v[48:63], v[224:227], v[152:155], v[48:63]
	ds_read_b128 v[224:227], v189 offset:40960
	v_exp_f32_e32 v179, v106
	v_exp_f32_e32 v180, v107
	v_exp_f32_e32 v232, v108
	v_exp_f32_e32 v233, v109
	s_waitcnt lgkmcnt(5)
	v_mfma_f32_32x32x16_bf16 v[32:47], v[228:231], v[152:155], v[32:47]
	ds_read_b128 v[228:231], v189 offset:45056
	v_exp_f32_e32 v234, v110
	v_exp_f32_e32 v235, v111
	v_add_f32_e32 v190, v190, v171
	v_add_f32_e32 v191, v191, v173
	s_waitcnt lgkmcnt(5)
	v_mfma_f32_32x32x16_bf16 v[16:31], v[208:211], v[152:155], v[16:31]
	ds_read_b128 v[208:211], v182 offset:0
	v_add_f32_e32 v190, v190, v179
	v_add_f32_e32 v191, v191, v180
	v_add_f32_e32 v190, v190, v232
	v_add_f32_e32 v191, v191, v233
	s_waitcnt lgkmcnt(5)
	v_mfma_f32_32x32x16_bf16 v[0:15], v[212:215], v[152:155], v[0:15]
	ds_read_b128 v[212:215], v182 offset:4096
	v_add_f32_e32 v190, v190, v234
	v_add_f32_e32 v191, v191, v235
	v_cvt_pk_bf16_f32 v148, v171, v173
	v_cvt_pk_bf16_f32 v149, v179, v180
	s_waitcnt lgkmcnt(5)
	v_mfma_f32_32x32x16_bf16 v[48:63], v[216:219], v[156:159], v[48:63]
	ds_read_b128 v[216:219], v183 offset:0
	v_cvt_pk_bf16_f32 v150, v232, v233
	v_cvt_pk_bf16_f32 v151, v234, v235
	v_exp_f32_e32 v171, v112
	v_exp_f32_e32 v173, v113
	s_waitcnt lgkmcnt(5)
	v_mfma_f32_32x32x16_bf16 v[32:47], v[220:223], v[156:159], v[32:47]
	ds_read_b128 v[220:223], v183 offset:4096
	v_exp_f32_e32 v179, v114
	v_exp_f32_e32 v180, v115
	v_exp_f32_e32 v232, v116
	v_exp_f32_e32 v233, v117
	s_waitcnt lgkmcnt(5)
	v_mfma_f32_32x32x16_bf16 v[16:31], v[224:227], v[156:159], v[16:31]
	ds_read_b128 v[224:227], v184 offset:0
	v_exp_f32_e32 v234, v118
	v_exp_f32_e32 v235, v119
	v_add_f32_e32 v190, v190, v171
	v_add_f32_e32 v191, v191, v173
	s_waitcnt lgkmcnt(5)
	v_mfma_f32_32x32x16_bf16 v[0:15], v[228:231], v[156:159], v[0:15]
	ds_read_b128 v[228:231], v184 offset:4096
	v_add_f32_e32 v190, v190, v179
	v_add_f32_e32 v191, v191, v180
	v_add_f32_e32 v190, v190, v232
	v_add_f32_e32 v191, v191, v233
	s_waitcnt lgkmcnt(5)
	v_mfma_f32_32x32x16_bf16 v[64:79], v[208:211], v[128:131], 0
	ds_read_b128 v[208:211], v185 offset:0
	v_add_f32_e32 v190, v190, v234
	v_add_f32_e32 v191, v191, v235
	v_cvt_pk_bf16_f32 v152, v171, v173
	v_cvt_pk_bf16_f32 v153, v179, v180
	s_waitcnt lgkmcnt(5)
	v_mfma_f32_32x32x16_bf16 v[80:95], v[212:215], v[128:131], 0
	ds_read_b128 v[212:215], v185 offset:4096
	v_cvt_pk_bf16_f32 v154, v232, v233
	v_cvt_pk_bf16_f32 v155, v234, v235
	v_exp_f32_e32 v171, v120
	v_exp_f32_e32 v173, v121
	s_waitcnt lgkmcnt(5)
	v_mfma_f32_32x32x16_bf16 v[64:79], v[216:219], v[132:135], v[64:79]
	ds_read_b128 v[216:219], v187 offset:49152
	v_exp_f32_e32 v179, v122
	v_exp_f32_e32 v180, v123
	v_exp_f32_e32 v232, v124
	v_exp_f32_e32 v233, v125
	s_waitcnt lgkmcnt(5)
	v_mfma_f32_32x32x16_bf16 v[80:95], v[220:223], v[132:135], v[80:95]
	ds_read_b128 v[220:223], v187 offset:53248
	v_exp_f32_e32 v234, v126
	v_exp_f32_e32 v235, v127
	v_add_f32_e32 v190, v190, v171
	s_waitcnt lgkmcnt(5)
	v_mfma_f32_32x32x16_bf16 v[64:79], v[224:227], v[136:139], v[64:79]
	ds_read_b128 v[224:227], v187 offset:57344
	v_add_f32_e32 v191, v191, v173
	v_add_f32_e32 v190, v190, v179
	v_add_f32_e32 v191, v191, v180
	s_waitcnt lgkmcnt(5)
	v_mfma_f32_32x32x16_bf16 v[80:95], v[228:231], v[136:139], v[80:95]
	ds_read_b128 v[228:231], v187 offset:61440
	v_add_f32_e32 v190, v190, v232
	v_add_f32_e32 v191, v191, v233
	v_add_f32_e32 v190, v190, v234
	s_waitcnt lgkmcnt(5)
	v_mfma_f32_32x32x16_bf16 v[64:79], v[208:211], v[140:143], v[64:79]
	ds_read_b128 v[208:211], v188 offset:49152
	v_add_f32_e32 v191, v191, v235
	v_cvt_pk_bf16_f32 v156, v171, v173
	v_cvt_pk_bf16_f32 v157, v179, v180
	s_waitcnt lgkmcnt(5)
	v_mfma_f32_32x32x16_bf16 v[80:95], v[212:215], v[140:143], v[80:95]
	ds_read_b128 v[212:215], v188 offset:53248
	v_cvt_pk_bf16_f32 v158, v232, v233
	v_cvt_pk_bf16_f32 v159, v234, v235
	v_add_f32_e32 v190, v190, v191
	v_cmp_ngt_f32_e32 vcc, 0x71800000, v190
	s_nop 4
	s_cbranch_vccnz .Lattn_redo_L2
	v_add_f32_e32 v167, v167, v190
	s_waitcnt vmcnt(4)
	s_barrier
	s_waitcnt lgkmcnt(5)
	v_mfma_f32_32x32x16_bf16 v[48:63], v[216:219], v[144:147], v[48:63]
	ds_read_b128 v[216:219], v188 offset:57344
	s_add_i32 s2, s42, 6
	s_and_b32 s2, s2, 31
	s_mul_i32 s2, s2, 0x44000
	s_add_i32 m0, s5, 49152
	s_add_u32 s40, s26, s2
	s_addc_u32 s41, s27, 0
	global_load_lds_dwordx4 v170, s[40:41]
	s_add_i32 m0, s5, 57344
	s_waitcnt lgkmcnt(5)
	v_mfma_f32_32x32x16_bf16 v[32:47], v[220:223], v[144:147], v[32:47]
	ds_read_b128 v[220:223], v188 offset:61440
	s_add_u32 s40, s40, 0x80
	s_addc_u32 s41, s41, 0
	global_load_lds_dwordx4 v170, s[40:41]
	s_add_i32 s2, s42, 5
	s_and_b32 s2, s2, 31
	s_lshl_b32 s2, s2, 7
	s_add_i32 m0, s5, 98304
	s_add_u32 s44, s10, s2
	s_waitcnt lgkmcnt(5)
	v_mfma_f32_32x32x16_bf16 v[16:31], v[224:227], v[144:147], v[16:31]
	ds_read_b128 v[224:227], v186 offset:49152
	s_addc_u32 s45, s11, 0
	global_load_lds_dwordx4 v172, s[44:45]
	s_add_i32 m0, s5, 106496
	s_add_u32 s44, s44, 0x204000
	s_addc_u32 s45, s45, 0
	global_load_lds_dwordx4 v172, s[44:45]
	s_waitcnt lgkmcnt(5)
	v_mfma_f32_32x32x16_bf16 v[0:15], v[228:231], v[144:147], v[0:15]
	ds_read_b128 v[228:231], v186 offset:53248
	v_exp_f32_e32 v171, v64
	v_exp_f32_e32 v173, v65
	v_exp_f32_e32 v179, v66
	v_exp_f32_e32 v180, v67
	s_waitcnt lgkmcnt(5)
	v_mfma_f32_32x32x16_bf16 v[48:63], v[208:211], v[148:151], v[48:63]
	ds_read_b128 v[208:211], v186 offset:57344
	v_exp_f32_e32 v232, v68
	v_exp_f32_e32 v233, v69
	v_exp_f32_e32 v234, v70
	v_exp_f32_e32 v235, v71
	s_waitcnt lgkmcnt(5)
	v_mfma_f32_32x32x16_bf16 v[32:47], v[212:215], v[148:151], v[32:47]
	ds_read_b128 v[212:215], v186 offset:61440
	v_add_f32_e32 v190, v171, v173
	v_add_f32_e32 v191, v179, v180
	v_add_f32_e32 v190, v190, v232
	v_add_f32_e32 v191, v191, v233
	s_waitcnt lgkmcnt(5)
	v_mfma_f32_32x32x16_bf16 v[16:31], v[216:219], v[148:151], v[16:31]
	ds_read_b128 v[216:219], v189 offset:49152
	v_add_f32_e32 v190, v190, v234
	v_add_f32_e32 v191, v191, v235
	v_cvt_pk_bf16_f32 v144, v171, v173
	v_cvt_pk_bf16_f32 v145, v179, v180
	s_waitcnt lgkmcnt(5)
	v_mfma_f32_32x32x16_bf16 v[0:15], v[220:223], v[148:151], v[0:15]
	ds_read_b128 v[220:223], v189 offset:53248
	v_cvt_pk_bf16_f32 v146, v232, v233
	v_cvt_pk_bf16_f32 v147, v234, v235
	v_exp_f32_e32 v171, v72
	v_exp_f32_e32 v173, v73
	s_waitcnt lgkmcnt(5)
	v_mfma_f32_32x32x16_bf16 v[48:63], v[224:227], v[152:155], v[48:63]
	ds_read_b128 v[224:227], v189 offset:57344
	v_exp_f32_e32 v179, v74
	v_exp_f32_e32 v180, v75
	v_exp_f32_e32 v232, v76
	v_exp_f32_e32 v233, v77
	s_waitcnt lgkmcnt(5)
	v_mfma_f32_32x32x16_bf16 v[32:47], v[228:231], v[152:155], v[32:47]
	ds_read_b128 v[228:231], v189 offset:61440
	v_exp_f32_e32 v234, v78
	v_exp_f32_e32 v235, v79
	v_add_f32_e32 v190, v190, v171
	v_add_f32_e32 v191, v191, v173
	s_waitcnt lgkmcnt(5)
	v_mfma_f32_32x32x16_bf16 v[16:31], v[208:211], v[152:155], v[16:31]
	ds_read_b128 v[208:211], v182 offset:16384
	v_add_f32_e32 v190, v190, v179
	v_add_f32_e32 v191, v191, v180
	v_add_f32_e32 v190, v190, v232
	v_add_f32_e32 v191, v191, v233
	s_waitcnt lgkmcnt(5)
	v_mfma_f32_32x32x16_bf16 v[0:15], v[212:215], v[152:155], v[0:15]
	ds_read_b128 v[212:215], v182 offset:20480
	v_add_f32_e32 v190, v190, v234
	v_add_f32_e32 v191, v191, v235
	v_cvt_pk_bf16_f32 v148, v171, v173
	v_cvt_pk_bf16_f32 v149, v179, v180
	s_waitcnt lgkmcnt(5)
	v_mfma_f32_32x32x16_bf16 v[48:63], v[216:219], v[156:159], v[48:63]
	ds_read_b128 v[216:219], v183 offset:16384
	v_cvt_pk_bf16_f32 v150, v232, v233
	v_cvt_pk_bf16_f32 v151, v234, v235
	v_exp_f32_e32 v171, v80
	v_exp_f32_e32 v173, v81
	s_waitcnt lgkmcnt(5)
	v_mfma_f32_32x32x16_bf16 v[32:47], v[220:223], v[156:159], v[32:47]
	ds_read_b128 v[220:223], v183 offset:20480
	v_exp_f32_e32 v179, v82
	v_exp_f32_e32 v180, v83
	v_exp_f32_e32 v232, v84
	v_exp_f32_e32 v233, v85
	s_waitcnt lgkmcnt(5)
	v_mfma_f32_32x32x16_bf16 v[16:31], v[224:227], v[156:159], v[16:31]
	ds_read_b128 v[224:227], v184 offset:16384
	v_exp_f32_e32 v234, v86
	v_exp_f32_e32 v235, v87
	v_add_f32_e32 v190, v190, v171
	v_add_f32_e32 v191, v191, v173
	s_waitcnt lgkmcnt(5)
	v_mfma_f32_32x32x16_bf16 v[0:15], v[228:231], v[156:159], v[0:15]
	ds_read_b128 v[228:231], v184 offset:20480
	v_add_f32_e32 v190, v190, v179
	v_add_f32_e32 v191, v191, v180
	v_add_f32_e32 v190, v190, v232
	v_add_f32_e32 v191, v191, v233
	s_waitcnt lgkmcnt(5)
	v_mfma_f32_32x32x16_bf16 v[96:111], v[208:211], v[128:131], 0
	ds_read_b128 v[208:211], v185 offset:16384
	v_add_f32_e32 v190, v190, v234
	v_add_f32_e32 v191, v191, v235
	v_cvt_pk_bf16_f32 v152, v171, v173
	v_cvt_pk_bf16_f32 v153, v179, v180
	s_waitcnt lgkmcnt(5)
	v_mfma_f32_32x32x16_bf16 v[112:127], v[212:215], v[128:131], 0
	ds_read_b128 v[212:215], v185 offset:20480
	v_cvt_pk_bf16_f32 v154, v232, v233
	v_cvt_pk_bf16_f32 v155, v234, v235
	v_exp_f32_e32 v171, v88
	v_exp_f32_e32 v173, v89
	s_waitcnt lgkmcnt(5)
	v_mfma_f32_32x32x16_bf16 v[96:111], v[216:219], v[132:135], v[96:111]
	ds_read_b128 v[216:219], v187 offset:0
	v_exp_f32_e32 v179, v90
	v_exp_f32_e32 v180, v91
	v_exp_f32_e32 v232, v92
	v_exp_f32_e32 v233, v93
	s_waitcnt lgkmcnt(5)
	v_mfma_f32_32x32x16_bf16 v[112:127], v[220:223], v[132:135], v[112:127]
	ds_read_b128 v[220:223], v187 offset:4096
	v_exp_f32_e32 v234, v94
	v_exp_f32_e32 v235, v95
	v_add_f32_e32 v190, v190, v171
	s_waitcnt lgkmcnt(5)
	v_mfma_f32_32x32x16_bf16 v[96:111], v[224:227], v[136:139], v[96:111]
	ds_read_b128 v[224:227], v187 offset:8192
	v_add_f32_e32 v191, v191, v173
	v_add_f32_e32 v190, v190, v179
	v_add_f32_e32 v191, v191, v180
	s_waitcnt lgkmcnt(5)
	v_mfma_f32_32x32x16_bf16 v[112:127], v[228:231], v[136:139], v[112:127]
	ds_read_b128 v[228:231], v187 offset:12288
	v_add_f32_e32 v190, v190, v232
	v_add_f32_e32 v191, v191, v233
	v_add_f32_e32 v190, v190, v234
	s_waitcnt lgkmcnt(5)
	v_mfma_f32_32x32x16_bf16 v[96:111], v[208:211], v[140:143], v[96:111]
	ds_read_b128 v[208:211], v188 offset:0
	v_add_f32_e32 v191, v191, v235
	v_cvt_pk_bf16_f32 v156, v171, v173
	v_cvt_pk_bf16_f32 v157, v179, v180
	s_waitcnt lgkmcnt(5)
	v_mfma_f32_32x32x16_bf16 v[112:127], v[212:215], v[140:143], v[112:127]
	ds_read_b128 v[212:215], v188 offset:4096
	v_cvt_pk_bf16_f32 v158, v232, v233
	v_cvt_pk_bf16_f32 v159, v234, v235
	v_add_f32_e32 v190, v190, v191
	v_cmp_ngt_f32_e32 vcc, 0x71800000, v190
	s_nop 4
	s_cbranch_vccnz .Lattn_redo_L3
	v_add_f32_e32 v167, v167, v190
	s_add_i32 s42, s42, 4
	s_add_i32 s47, s47, -1
	s_cmp_lg_u32 s47, 0
	s_cbranch_scc1 .Lattn_loop_f
	s_waitcnt vmcnt(4)
	s_barrier
	s_waitcnt lgkmcnt(5)
	v_mfma_f32_32x32x16_bf16 v[48:63], v[216:219], v[144:147], v[48:63]
	ds_read_b128 v[216:219], v188 offset:8192
	s_add_i32 s2, s42, 2
	s_and_b32 s2, s2, 31
	s_lshl_b32 s2, s2, 7
	s_add_i32 m0, s5, 114688
	s_add_u32 s44, s10, s2
	s_addc_u32 s45, s11, 0
	global_load_lds_dwordx4 v172, s[44:45]
	s_add_i32 m0, s5, 122880
	s_waitcnt lgkmcnt(5)
	v_mfma_f32_32x32x16_bf16 v[32:47], v[220:223], v[144:147], v[32:47]
	ds_read_b128 v[220:223], v188 offset:12288
	s_add_u32 s44, s44, 0x204000
	s_addc_u32 s45, s45, 0
	global_load_lds_dwordx4 v172, s[44:45]
	s_waitcnt lgkmcnt(5)
	v_mfma_f32_32x32x16_bf16 v[16:31], v[224:227], v[144:147], v[16:31]
	ds_read_b128 v[224:227], v186 offset:0
	s_waitcnt lgkmcnt(5)
	v_mfma_f32_32x32x16_bf16 v[0:15], v[228:231], v[144:147], v[0:15]
	ds_read_b128 v[228:231], v186 offset:4096
	v_exp_f32_e32 v171, v96
	v_exp_f32_e32 v173, v97
	v_exp_f32_e32 v179, v98
	v_exp_f32_e32 v180, v99
	s_waitcnt lgkmcnt(5)
	v_mfma_f32_32x32x16_bf16 v[48:63], v[208:211], v[148:151], v[48:63]
	ds_read_b128 v[208:211], v186 offset:8192
	v_exp_f32_e32 v232, v100
	v_exp_f32_e32 v233, v101
	v_exp_f32_e32 v234, v102
	v_exp_f32_e32 v235, v103
	s_waitcnt lgkmcnt(5)
	v_mfma_f32_32x32x16_bf16 v[32:47], v[212:215], v[148:151], v[32:47]
	ds_read_b128 v[212:215], v186 offset:12288
	v_add_f32_e32 v190, v171, v173
	v_add_f32_e32 v191, v179, v180
	v_add_f32_e32 v190, v190, v232
	v_add_f32_e32 v191, v191, v233
	s_waitcnt lgkmcnt(5)
	v_mfma_f32_32x32x16_bf16 v[16:31], v[216:219], v[148:151], v[16:31]
	ds_read_b128 v[216:219], v189 offset:0
	v_add_f32_e32 v190, v190, v234
	v_add_f32_e32 v191, v191, v235
	v_cvt_pk_bf16_f32 v144, v171, v173
	v_cvt_pk_bf16_f32 v145, v179, v180
	s_waitcnt lgkmcnt(5)
	v_mfma_f32_32x32x16_bf16 v[0:15], v[220:223], v[148:151], v[0:15]
	ds_read_b128 v[220:223], v189 offset:4096
	v_cvt_pk_bf16_f32 v146, v232, v233
	v_cvt_pk_bf16_f32 v147, v234, v235
	v_exp_f32_e32 v171, v104
	v_exp_f32_e32 v173, v105
	s_waitcnt lgkmcnt(5)
	v_mfma_f32_32x32x16_bf16 v[48:63], v[224:227], v[152:155], v[48:63]
	ds_read_b128 v[224:227], v189 offset:8192
	v_exp_f32_e32 v179, v106
	v_exp_f32_e32 v180, v107
	v_exp_f32_e32 v232, v108
	v_exp_f32_e32 v233, v109
	s_waitcnt lgkmcnt(5)
	v_mfma_f32_32x32x16_bf16 v[32:47], v[228:231], v[152:155], v[32:47]
	ds_read_b128 v[228:231], v189 offset:12288
	v_exp_f32_e32 v234, v110
	v_exp_f32_e32 v235, v111
	v_add_f32_e32 v190, v190, v171
	v_add_f32_e32 v191, v191, v173
	s_waitcnt lgkmcnt(5)
	v_mfma_f32_32x32x16_bf16 v[16:31], v[208:211], v[152:155], v[16:31]
	ds_read_b128 v[208:211], v182 offset:32768
	v_add_f32_e32 v190, v190, v179
	v_add_f32_e32 v191, v191, v180
	v_add_f32_e32 v190, v190, v232
	v_add_f32_e32 v191, v191, v233
	s_waitcnt lgkmcnt(5)
	v_mfma_f32_32x32x16_bf16 v[0:15], v[212:215], v[152:155], v[0:15]
	ds_read_b128 v[212:215], v182 offset:36864
	v_add_f32_e32 v190, v190, v234
	v_add_f32_e32 v191, v191, v235
	v_cvt_pk_bf16_f32 v148, v171, v173
	v_cvt_pk_bf16_f32 v149, v179, v180
	s_waitcnt lgkmcnt(5)
	v_mfma_f32_32x32x16_bf16 v[48:63], v[216:219], v[156:159], v[48:63]
	ds_read_b128 v[216:219], v183 offset:32768
	v_cvt_pk_bf16_f32 v150, v232, v233
	v_cvt_pk_bf16_f32 v151, v234, v235
	v_exp_f32_e32 v171, v112
	v_exp_f32_e32 v173, v113
	s_waitcnt lgkmcnt(5)
	v_mfma_f32_32x32x16_bf16 v[32:47], v[220:223], v[156:159], v[32:47]
	ds_read_b128 v[220:223], v183 offset:36864
	v_exp_f32_e32 v179, v114
	v_exp_f32_e32 v180, v115
	v_exp_f32_e32 v232, v116
	v_exp_f32_e32 v233, v117
	s_waitcnt lgkmcnt(5)
	v_mfma_f32_32x32x16_bf16 v[16:31], v[224:227], v[156:159], v[16:31]
	ds_read_b128 v[224:227], v184 offset:32768
	v_exp_f32_e32 v234, v118
	v_exp_f32_e32 v235, v119
	v_add_f32_e32 v190, v190, v171
	v_add_f32_e32 v191, v191, v173
	s_waitcnt lgkmcnt(5)
	v_mfma_f32_32x32x16_bf16 v[0:15], v[228:231], v[156:159], v[0:15]
	ds_read_b128 v[228:231], v184 offset:36864
	v_add_f32_e32 v190, v190, v179
	v_add_f32_e32 v191, v191, v180
	v_add_f32_e32 v190, v190, v232
	v_add_f32_e32 v191, v191, v233
	s_waitcnt lgkmcnt(5)
	v_mfma_f32_32x32x16_bf16 v[64:79], v[208:211], v[128:131], 0
	ds_read_b128 v[208:211], v185 offset:32768
	v_add_f32_e32 v190, v190, v234
	v_add_f32_e32 v191, v191, v235
	v_cvt_pk_bf16_f32 v152, v171, v173
	v_cvt_pk_bf16_f32 v153, v179, v180
	s_waitcnt lgkmcnt(5)
	v_mfma_f32_32x32x16_bf16 v[80:95], v[212:215], v[128:131], 0
	ds_read_b128 v[212:215], v185 offset:36864
	v_cvt_pk_bf16_f32 v154, v232, v233
	v_cvt_pk_bf16_f32 v155, v234, v235
	v_exp_f32_e32 v171, v120
	v_exp_f32_e32 v173, v121
	s_waitcnt lgkmcnt(5)
	v_mfma_f32_32x32x16_bf16 v[64:79], v[216:219], v[132:135], v[64:79]
	ds_read_b128 v[216:219], v187 offset:16384
	v_exp_f32_e32 v179, v122
	v_exp_f32_e32 v180, v123
	v_exp_f32_e32 v232, v124
	v_exp_f32_e32 v233, v125
	s_waitcnt lgkmcnt(5)
	v_mfma_f32_32x32x16_bf16 v[80:95], v[220:223], v[132:135], v[80:95]
	ds_read_b128 v[220:223], v187 offset:20480
	v_exp_f32_e32 v234, v126
	v_exp_f32_e32 v235, v127
	v_add_f32_e32 v190, v190, v171
	s_waitcnt lgkmcnt(5)
	v_mfma_f32_32x32x16_bf16 v[64:79], v[224:227], v[136:139], v[64:79]
	ds_read_b128 v[224:227], v187 offset:24576
	v_add_f32_e32 v191, v191, v173
	v_add_f32_e32 v190, v190, v179
	v_add_f32_e32 v191, v191, v180
	s_waitcnt lgkmcnt(5)
	v_mfma_f32_32x32x16_bf16 v[80:95], v[228:231], v[136:139], v[80:95]
	ds_read_b128 v[228:231], v187 offset:28672
	v_add_f32_e32 v190, v190, v232
	v_add_f32_e32 v191, v191, v233
	v_add_f32_e32 v190, v190, v234
	s_waitcnt lgkmcnt(5)
	v_mfma_f32_32x32x16_bf16 v[64:79], v[208:211], v[140:143], v[64:79]
	ds_read_b128 v[208:211], v188 offset:16384
	v_add_f32_e32 v191, v191, v235
	v_cvt_pk_bf16_f32 v156, v171, v173
	v_cvt_pk_bf16_f32 v157, v179, v180
	s_waitcnt lgkmcnt(5)
	v_mfma_f32_32x32x16_bf16 v[80:95], v[212:215], v[140:143], v[80:95]
	ds_read_b128 v[212:215], v188 offset:20480
	v_cvt_pk_bf16_f32 v158, v232, v233
	v_cvt_pk_bf16_f32 v159, v234, v235
	v_add_f32_e32 v190, v190, v191
	v_cmp_ngt_f32_e32 vcc, 0x71800000, v190
	s_nop 4
	s_cbranch_vccnz .Lattn_redo_T29
	v_add_f32_e32 v167, v167, v190
	s_waitcnt vmcnt(2)
	s_barrier
	s_waitcnt lgkmcnt(5)
	v_mfma_f32_32x32x16_bf16 v[48:63], v[216:219], v[144:147], v[48:63]
	ds_read_b128 v[216:219], v188 offset:24576
	v_readlane_b32 s2, v253, 52
	s_add_i32 s36, s46, 1
	s_mul_i32 s36, s36, s56
	s_add_i32 s36, s36, s0
	s_cmp_lg_u32 s2, 0
	s_cselect_b32 s2, 1, 0
	s_cmpk_lt_i32 s36, 0x400
	s_cselect_b32 s36, 1, 0
	s_and_b32 s35, s2, s36
	s_waitcnt lgkmcnt(5)
	v_mfma_f32_32x32x16_bf16 v[32:47], v[220:223], v[144:147], v[32:47]
	ds_read_b128 v[220:223], v188 offset:28672
	s_cmp_lg_u32 s35, 0
	s_cbranch_scc0 .Lattn_pfka_f
	s_add_i32 s2, s31, 0
	s_and_b32 s2, s2, 31
	s_mul_i32 s2, s2, 0x44000
	s_add_i32 m0, s5, 0
	s_add_u32 s40, s26, s2
	s_addc_u32 s41, s27, 0
	s_add_u32 s40, s40, 0x1100000
	s_addc_u32 s41, s41, 0
	global_load_lds_dwordx4 v170, s[40:41]
	s_add_i32 m0, s5, 8192
	s_add_u32 s40, s40, 0x80
	s_addc_u32 s41, s41, 0
	global_load_lds_dwordx4 v170, s[40:41]
.Lattn_pfka_f:
	s_waitcnt lgkmcnt(5)
	v_mfma_f32_32x32x16_bf16 v[16:31], v[224:227], v[144:147], v[16:31]
	ds_read_b128 v[224:227], v186 offset:16384
	s_cmp_lg_u32 s35, 0
	s_cbranch_scc0 .Lattn_pfkb_f
	s_add_i32 s2, s31, 1
	s_and_b32 s2, s2, 31
	s_mul_i32 s2, s2, 0x44000
	s_add_i32 m0, s5, 16384
	s_add_u32 s40, s26, s2
	s_addc_u32 s41, s27, 0
	s_add_u32 s40, s40, 0x1100000
	s_addc_u32 s41, s41, 0
	global_load_lds_dwordx4 v170, s[40:41]
	s_add_i32 m0, s5, 24576
	s_add_u32 s40, s40, 0x80
	s_addc_u32 s41, s41, 0
	global_load_lds_dwordx4 v170, s[40:41]
.Lattn_pfkb_f:
	s_waitcnt lgkmcnt(5)
	v_mfma_f32_32x32x16_bf16 v[0:15], v[228:231], v[144:147], v[0:15]
	ds_read_b128 v[228:231], v186 offset:20480
	s_cmp_lg_u32 s35, 0
	s_cbranch_scc0 .Lattn_pfvt_f
	s_add_i32 s2, s31, 0
	s_and_b32 s2, s2, 31
	s_lshl_b32 s2, s2, 7
	s_add_i32 m0, s5, 65536
	s_add_u32 s44, s10, s2
	s_addc_u32 s45, s11, 0
	s_add_u32 s44, s44, 0x2000
	s_addc_u32 s45, s45, 0
	global_load_lds_dwordx4 v172, s[44:45]
	s_add_i32 m0, s5, 73728
	s_add_u32 s44, s44, 0x204000
	s_addc_u32 s45, s45, 0
	global_load_lds_dwordx4 v172, s[44:45]
.Lattn_pfvt_f:
	v_exp_f32_e32 v171, v64
	v_exp_f32_e32 v173, v65
	v_exp_f32_e32 v179, v66
	v_exp_f32_e32 v180, v67
	s_waitcnt lgkmcnt(5)
	v_mfma_f32_32x32x16_bf16 v[48:63], v[208:211], v[148:151], v[48:63]
	ds_read_b128 v[208:211], v186 offset:24576
	v_exp_f32_e32 v232, v68
	v_exp_f32_e32 v233, v69
	v_exp_f32_e32 v234, v70
	v_exp_f32_e32 v235, v71
	s_waitcnt lgkmcnt(5)
	v_mfma_f32_32x32x16_bf16 v[32:47], v[212:215], v[148:151], v[32:47]
	ds_read_b128 v[212:215], v186 offset:28672
	v_add_f32_e32 v190, v171, v173
	v_add_f32_e32 v191, v179, v180
	v_add_f32_e32 v190, v190, v232
	v_add_f32_e32 v191, v191, v233
	s_waitcnt lgkmcnt(5)
	v_mfma_f32_32x32x16_bf16 v[16:31], v[216:219], v[148:151], v[16:31]
	ds_read_b128 v[216:219], v189 offset:16384
	v_add_f32_e32 v190, v190, v234
	v_add_f32_e32 v191, v191, v235
	v_cvt_pk_bf16_f32 v144, v171, v173
	v_cvt_pk_bf16_f32 v145, v179, v180
	s_waitcnt lgkmcnt(5)
	v_mfma_f32_32x32x16_bf16 v[0:15], v[220:223], v[148:151], v[0:15]
	ds_read_b128 v[220:223], v189 offset:20480
	v_cvt_pk_bf16_f32 v146, v232, v233
	v_cvt_pk_bf16_f32 v147, v234, v235
	v_exp_f32_e32 v171, v72
	v_exp_f32_e32 v173, v73
	s_waitcnt lgkmcnt(5)
	v_mfma_f32_32x32x16_bf16 v[48:63], v[224:227], v[152:155], v[48:63]
	ds_read_b128 v[224:227], v189 offset:24576
	v_exp_f32_e32 v179, v74
	v_exp_f32_e32 v180, v75
	v_exp_f32_e32 v232, v76
	v_exp_f32_e32 v233, v77
	s_waitcnt lgkmcnt(5)
	v_mfma_f32_32x32x16_bf16 v[32:47], v[228:231], v[152:155], v[32:47]
	ds_read_b128 v[228:231], v189 offset:28672
	v_exp_f32_e32 v234, v78
	v_exp_f32_e32 v235, v79
	v_add_f32_e32 v190, v190, v171
	v_add_f32_e32 v191, v191, v173
	s_waitcnt lgkmcnt(5)
	v_mfma_f32_32x32x16_bf16 v[16:31], v[208:211], v[152:155], v[16:31]
	ds_read_b128 v[208:211], v182 offset:49152
	v_add_f32_e32 v190, v190, v179
	v_add_f32_e32 v191, v191, v180
	v_add_f32_e32 v190, v190, v232
	v_add_f32_e32 v191, v191, v233
	s_waitcnt lgkmcnt(5)
	v_mfma_f32_32x32x16_bf16 v[0:15], v[212:215], v[152:155], v[0:15]
	ds_read_b128 v[212:215], v182 offset:53248
	v_add_f32_e32 v190, v190, v234
	v_add_f32_e32 v191, v191, v235
	v_cvt_pk_bf16_f32 v148, v171, v173
	v_cvt_pk_bf16_f32 v149, v179, v180
	s_waitcnt lgkmcnt(5)
	v_mfma_f32_32x32x16_bf16 v[48:63], v[216:219], v[156:159], v[48:63]
	ds_read_b128 v[216:219], v183 offset:49152
	v_cvt_pk_bf16_f32 v150, v232, v233
	v_cvt_pk_bf16_f32 v151, v234, v235
	v_exp_f32_e32 v171, v80
	v_exp_f32_e32 v173, v81
	s_waitcnt lgkmcnt(5)
	v_mfma_f32_32x32x16_bf16 v[32:47], v[220:223], v[156:159], v[32:47]
	ds_read_b128 v[220:223], v183 offset:53248
	v_exp_f32_e32 v179, v82
	v_exp_f32_e32 v180, v83
	v_exp_f32_e32 v232, v84
	v_exp_f32_e32 v233, v85
	s_waitcnt lgkmcnt(5)
	v_mfma_f32_32x32x16_bf16 v[16:31], v[224:227], v[156:159], v[16:31]
	ds_read_b128 v[224:227], v184 offset:49152
	v_exp_f32_e32 v234, v86
	v_exp_f32_e32 v235, v87
	v_add_f32_e32 v190, v190, v171
	v_add_f32_e32 v191, v191, v173
	s_waitcnt lgkmcnt(5)
	v_mfma_f32_32x32x16_bf16 v[0:15], v[228:231], v[156:159], v[0:15]
	ds_read_b128 v[228:231], v184 offset:53248
	v_add_f32_e32 v190, v190, v179
	v_add_f32_e32 v191, v191, v180
	v_add_f32_e32 v190, v190, v232
	v_add_f32_e32 v191, v191, v233
	s_waitcnt lgkmcnt(5)
	v_mfma_f32_32x32x16_bf16 v[96:111], v[208:211], v[128:131], 0
	ds_read_b128 v[208:211], v185 offset:49152
	v_add_f32_e32 v190, v190, v234
	v_add_f32_e32 v191, v191, v235
	v_cvt_pk_bf16_f32 v152, v171, v173
	v_cvt_pk_bf16_f32 v153, v179, v180
	s_waitcnt lgkmcnt(5)
	v_mfma_f32_32x32x16_bf16 v[112:127], v[212:215], v[128:131], 0
	ds_read_b128 v[212:215], v185 offset:53248
	v_cvt_pk_bf16_f32 v154, v232, v233
	v_cvt_pk_bf16_f32 v155, v234, v235
	v_exp_f32_e32 v171, v88
	v_exp_f32_e32 v173, v89
	s_waitcnt lgkmcnt(5)
	v_mfma_f32_32x32x16_bf16 v[96:111], v[216:219], v[132:135], v[96:111]
	ds_read_b128 v[216:219], v187 offset:32768
	v_exp_f32_e32 v179, v90
	v_exp_f32_e32 v180, v91
	v_exp_f32_e32 v232, v92
	v_exp_f32_e32 v233, v93
	s_waitcnt lgkmcnt(5)
	v_mfma_f32_32x32x16_bf16 v[112:127], v[220:223], v[132:135], v[112:127]
	ds_read_b128 v[220:223], v187 offset:36864
	v_exp_f32_e32 v234, v94
	v_exp_f32_e32 v235, v95
	v_add_f32_e32 v190, v190, v171
	s_waitcnt lgkmcnt(5)
	v_mfma_f32_32x32x16_bf16 v[96:111], v[224:227], v[136:139], v[96:111]
	ds_read_b128 v[224:227], v187 offset:40960
	v_add_f32_e32 v191, v191, v173
	v_add_f32_e32 v190, v190, v179
	v_add_f32_e32 v191, v191, v180
	s_waitcnt lgkmcnt(5)
	v_mfma_f32_32x32x16_bf16 v[112:127], v[228:231], v[136:139], v[112:127]
	ds_read_b128 v[228:231], v187 offset:45056
	v_add_f32_e32 v190, v190, v232
	v_add_f32_e32 v191, v191, v233
	v_add_f32_e32 v190, v190, v234
	s_waitcnt lgkmcnt(5)
	v_mfma_f32_32x32x16_bf16 v[96:111], v[208:211], v[140:143], v[96:111]
	ds_read_b128 v[208:211], v188 offset:32768
	v_add_f32_e32 v191, v191, v235
	v_cvt_pk_bf16_f32 v156, v171, v173
	v_cvt_pk_bf16_f32 v157, v179, v180
	s_waitcnt lgkmcnt(5)
	v_mfma_f32_32x32x16_bf16 v[112:127], v[212:215], v[140:143], v[112:127]
	ds_read_b128 v[212:215], v188 offset:36864
	v_cvt_pk_bf16_f32 v158, v232, v233
	v_cvt_pk_bf16_f32 v159, v234, v235
	v_add_f32_e32 v190, v190, v191
	v_cmp_ngt_f32_e32 vcc, 0x71800000, v190
	s_nop 4
	s_cbranch_vccnz .Lattn_redo_T30
	v_add_f32_e32 v167, v167, v190
	s_cmp_lg_u32 s35, 0
	s_cbranch_scc1 .Lattn_w6_opt
	s_waitcnt vmcnt(0)
	s_branch .Lattn_wd_opt
.Lattn_w6_opt:
	s_waitcnt vmcnt(6)
.Lattn_wd_opt:
	s_barrier
	s_waitcnt lgkmcnt(5)
	v_mfma_f32_32x32x16_bf16 v[48:63], v[216:219], v[144:147], v[48:63]
	ds_read_b128 v[216:219], v188 offset:40960
	s_cmp_lg_u32 s35, 0
	s_cbranch_scc0 .Lattn_pfq_f
	s_movk_i32 s2, 0x1100
	s_lshl_b32 s36, s14, 1
	v_mad_u32_u24 v72, v168, s2, v192
	s_add_i32 s36, s36, s30
	s_add_i32 s36, s36, 0x1100000
	s_nop 0
	v_add_u32_e32 v72, s36, v72
	s_nop 0
	global_load_dwordx4 v[64:67], v72, s[6:7]
	global_load_dwordx4 v[68:71], v72, s[6:7] offset:32
	global_load_dwordx4 v[136:139], v72, s[6:7] offset:64
	global_load_dwordx4 v[140:143], v72, s[6:7] offset:96
.Lattn_pfq_f:
	s_waitcnt lgkmcnt(5)
	v_mfma_f32_32x32x16_bf16 v[32:47], v[220:223], v[144:147], v[32:47]
	ds_read_b128 v[220:223], v188 offset:45056
	s_waitcnt lgkmcnt(5)
	v_mfma_f32_32x32x16_bf16 v[16:31], v[224:227], v[144:147], v[16:31]
	ds_read_b128 v[224:227], v186 offset:32768
	s_waitcnt lgkmcnt(5)
	v_mfma_f32_32x32x16_bf16 v[0:15], v[228:231], v[144:147], v[0:15]
	ds_read_b128 v[228:231], v186 offset:36864
	v_exp_f32_e32 v171, v96
	v_exp_f32_e32 v173, v97
	v_exp_f32_e32 v179, v98
	v_exp_f32_e32 v180, v99
	v_exp_f32_e32 v232, v100
	v_exp_f32_e32 v233, v101
	v_exp_f32_e32 v234, v102
	s_waitcnt lgkmcnt(5)
	v_mfma_f32_32x32x16_bf16 v[48:63], v[208:211], v[148:151], v[48:63]
	ds_read_b128 v[208:211], v186 offset:40960
	v_exp_f32_e32 v235, v103
	v_add_f32_e32 v190, v171, v173
	v_add_f32_e32 v191, v179, v180
	v_add_f32_e32 v190, v190, v232
	v_add_f32_e32 v191, v191, v233
	v_add_f32_e32 v190, v190, v234
	s_waitcnt lgkmcnt(5)
	v_mfma_f32_32x32x16_bf16 v[32:47], v[212:215], v[148:151], v[32:47]
	ds_read_b128 v[212:215], v186 offset:45056
	v_add_f32_e32 v191, v191, v235
	v_cvt_pk_bf16_f32 v144, v171, v173
	v_cvt_pk_bf16_f32 v145, v179, v180
	v_cvt_pk_bf16_f32 v146, v232, v233
	v_cvt_pk_bf16_f32 v147, v234, v235
	s_waitcnt lgkmcnt(5)
	v_mfma_f32_32x32x16_bf16 v[16:31], v[216:219], v[148:151], v[16:31]
	ds_read_b128 v[216:219], v189 offset:32768
	s_waitcnt lgkmcnt(5)
	v_mfma_f32_32x32x16_bf16 v[0:15], v[220:223], v[148:151], v[0:15]
	ds_read_b128 v[220:223], v189 offset:36864
	v_exp_f32_e32 v171, v104
	v_exp_f32_e32 v173, v105
	v_exp_f32_e32 v179, v106
	v_exp_f32_e32 v180, v107
	v_exp_f32_e32 v232, v108
	v_exp_f32_e32 v233, v109
	v_exp_f32_e32 v234, v110
	s_waitcnt lgkmcnt(5)
	v_mfma_f32_32x32x16_bf16 v[48:63], v[224:227], v[152:155], v[48:63]
	ds_read_b128 v[224:227], v189 offset:40960
	v_exp_f32_e32 v235, v111
	v_add_f32_e32 v190, v190, v171
	v_add_f32_e32 v191, v191, v173
	v_add_f32_e32 v190, v190, v179
	v_add_f32_e32 v191, v191, v180
	v_add_f32_e32 v190, v190, v232
	v_add_f32_e32 v191, v191, v233
	s_waitcnt lgkmcnt(5)
	v_mfma_f32_32x32x16_bf16 v[32:47], v[228:231], v[152:155], v[32:47]
	ds_read_b128 v[228:231], v189 offset:45056
	v_add_f32_e32 v190, v190, v234
	v_add_f32_e32 v191, v191, v235
	v_cvt_pk_bf16_f32 v148, v171, v173
	v_cvt_pk_bf16_f32 v149, v179, v180
	v_cvt_pk_bf16_f32 v150, v232, v233
	v_cvt_pk_bf16_f32 v151, v234, v235
	s_waitcnt lgkmcnt(5)
	v_mfma_f32_32x32x16_bf16 v[16:31], v[208:211], v[152:155], v[16:31]
	ds_read_b128 v[208:211], v187 offset:49152
	s_waitcnt lgkmcnt(5)
	v_mfma_f32_32x32x16_bf16 v[0:15], v[212:215], v[152:155], v[0:15]
	ds_read_b128 v[212:215], v187 offset:53248
	v_exp_f32_e32 v171, v112
	v_exp_f32_e32 v173, v113
	v_exp_f32_e32 v179, v114
	v_exp_f32_e32 v180, v115
	v_exp_f32_e32 v232, v116
	v_exp_f32_e32 v233, v117
	v_exp_f32_e32 v234, v118
	v_exp_f32_e32 v235, v119
	v_add_f32_e32 v190, v190, v171
	s_waitcnt lgkmcnt(5)
	v_mfma_f32_32x32x16_bf16 v[48:63], v[216:219], v[156:159], v[48:63]
	ds_read_b128 v[216:219], v187 offset:57344
	v_add_f32_e32 v191, v191, v173
	v_add_f32_e32 v190, v190, v179
	v_add_f32_e32 v191, v191, v180
	v_add_f32_e32 v190, v190, v232
	v_add_f32_e32 v191, v191, v233
	v_add_f32_e32 v190, v190, v234
	v_add_f32_e32 v191, v191, v235
	v_cvt_pk_bf16_f32 v152, v171, v173
	s_waitcnt lgkmcnt(5)
	v_mfma_f32_32x32x16_bf16 v[32:47], v[220:223], v[156:159], v[32:47]
	ds_read_b128 v[220:223], v187 offset:61440
	v_cvt_pk_bf16_f32 v153, v179, v180
	v_cvt_pk_bf16_f32 v154, v232, v233
	v_cvt_pk_bf16_f32 v155, v234, v235
	s_waitcnt lgkmcnt(5)
	v_mfma_f32_32x32x16_bf16 v[16:31], v[224:227], v[156:159], v[16:31]
	ds_read_b128 v[224:227], v188 offset:49152
	s_waitcnt lgkmcnt(5)
	v_mfma_f32_32x32x16_bf16 v[0:15], v[228:231], v[156:159], v[0:15]
	ds_read_b128 v[228:231], v188 offset:53248
	v_exp_f32_e32 v171, v120
	v_exp_f32_e32 v173, v121
	v_exp_f32_e32 v179, v122
	v_exp_f32_e32 v180, v123
	v_exp_f32_e32 v232, v124
	v_exp_f32_e32 v233, v125
	v_exp_f32_e32 v234, v126
	v_exp_f32_e32 v235, v127
	v_add_f32_e32 v190, v190, v171
	v_add_f32_e32 v191, v191, v173
	v_add_f32_e32 v190, v190, v179
	v_add_f32_e32 v191, v191, v180
	v_add_f32_e32 v190, v190, v232
	v_add_f32_e32 v191, v191, v233
	v_add_f32_e32 v190, v190, v234
	v_add_f32_e32 v191, v191, v235
	v_cvt_pk_bf16_f32 v156, v171, v173
	v_cvt_pk_bf16_f32 v157, v179, v180
	v_cvt_pk_bf16_f32 v158, v232, v233
	v_cvt_pk_bf16_f32 v159, v234, v235
	v_add_f32_e32 v190, v190, v191
	v_cmp_ngt_f32_e32 vcc, 0x71800000, v190
	s_nop 4
	s_cbranch_vccnz .Lattn_redo_T31
	v_add_f32_e32 v167, v167, v190
.Lattn_final:
	s_waitcnt lgkmcnt(5)
	v_mfma_f32_32x32x16_bf16 v[48:63], v[208:211], v[144:147], v[48:63]
	ds_read_b128 v[208:211], v188 offset:57344
	s_waitcnt lgkmcnt(5)
	v_mfma_f32_32x32x16_bf16 v[32:47], v[212:215], v[144:147], v[32:47]
	ds_read_b128 v[212:215], v188 offset:61440
	s_waitcnt lgkmcnt(5)
	v_mfma_f32_32x32x16_bf16 v[16:31], v[216:219], v[144:147], v[16:31]
	ds_read_b128 v[216:219], v186 offset:49152
	s_waitcnt lgkmcnt(5)
	v_mfma_f32_32x32x16_bf16 v[0:15], v[220:223], v[144:147], v[0:15]
	ds_read_b128 v[220:223], v186 offset:53248
	s_waitcnt lgkmcnt(5)
	v_mfma_f32_32x32x16_bf16 v[48:63], v[224:227], v[148:151], v[48:63]
	ds_read_b128 v[224:227], v186 offset:57344
	s_waitcnt lgkmcnt(5)
	v_mfma_f32_32x32x16_bf16 v[32:47], v[228:231], v[148:151], v[32:47]
	ds_read_b128 v[228:231], v186 offset:61440
	s_waitcnt lgkmcnt(5)
	v_mfma_f32_32x32x16_bf16 v[16:31], v[208:211], v[148:151], v[16:31]
	ds_read_b128 v[208:211], v189 offset:49152
	s_waitcnt lgkmcnt(5)
	v_mfma_f32_32x32x16_bf16 v[0:15], v[212:215], v[148:151], v[0:15]
	ds_read_b128 v[212:215], v189 offset:53248
	s_waitcnt lgkmcnt(5)
	v_mfma_f32_32x32x16_bf16 v[48:63], v[216:219], v[152:155], v[48:63]
	ds_read_b128 v[216:219], v189 offset:57344
	s_waitcnt lgkmcnt(5)
	v_mfma_f32_32x32x16_bf16 v[32:47], v[220:223], v[152:155], v[32:47]
	ds_read_b128 v[220:223], v189 offset:61440
	s_waitcnt lgkmcnt(5)
	v_mfma_f32_32x32x16_bf16 v[16:31], v[224:227], v[152:155], v[16:31]
	s_waitcnt lgkmcnt(4)
	v_mfma_f32_32x32x16_bf16 v[0:15], v[228:231], v[152:155], v[0:15]
	s_waitcnt lgkmcnt(3)
	v_mfma_f32_32x32x16_bf16 v[48:63], v[208:211], v[156:159], v[48:63]
	s_waitcnt lgkmcnt(2)
	v_mfma_f32_32x32x16_bf16 v[32:47], v[212:215], v[156:159], v[32:47]
	s_waitcnt lgkmcnt(1)
	v_mfma_f32_32x32x16_bf16 v[16:31], v[216:219], v[156:159], v[16:31]
	s_waitcnt lgkmcnt(0)
	v_mfma_f32_32x32x16_bf16 v[0:15], v[220:223], v[156:159], v[0:15]
	s_nop 15
	s_nop 7
	s_cmp_lg_u32 s35, 0
	s_cbranch_scc0 .Lattn_nocopy
	s_waitcnt vmcnt(2)
	v_mov_b32_e32 v144, v64
	v_mov_b32_e32 v145, v65
	v_mov_b32_e32 v146, v66
	v_mov_b32_e32 v147, v67
	v_mov_b32_e32 v148, v68
	v_mov_b32_e32 v149, v69
	v_mov_b32_e32 v150, v70
	v_mov_b32_e32 v151, v71
.Lattn_nocopy:
	v_mov_b32_e32 v64, v167
	s_branch .Lattn_end

.Lattn_noresc_T29:
.Lattn_top_T30:
	s_waitcnt vmcnt(2)
	s_barrier
	s_waitcnt lgkmcnt(5)
	v_mfma_f32_32x32x16_bf16 v[48:63], v[216:219], v[144:147], v[48:63]
	ds_read_b128 v[216:219], v188 offset:24576
	s_nop 3
	v_max3_f32 v254, v64, v65, v66
	v_max3_f32 v255, v80, v81, v82
	v_max3_f32 v254, v254, v67, v68
	v_max3_f32 v255, v255, v83, v84
	v_max3_f32 v254, v254, v69, v70
	v_max3_f32 v255, v255, v85, v86
	v_max3_f32 v254, v254, v71, v72
	s_waitcnt lgkmcnt(5)
	v_mfma_f32_32x32x16_bf16 v[32:47], v[220:223], v[144:147], v[32:47]
	ds_read_b128 v[220:223], v188 offset:28672
	v_max3_f32 v255, v255, v87, v88
	v_max3_f32 v254, v254, v73, v74
	v_max3_f32 v255, v255, v89, v90
	v_max3_f32 v254, v254, v75, v76
	v_max3_f32 v255, v255, v91, v92
	v_max3_f32 v254, v254, v77, v78
	v_max3_f32 v255, v255, v93, v94
	v_max3_f32 v254, v254, v79, v95
	s_waitcnt lgkmcnt(5)
	v_mfma_f32_32x32x16_bf16 v[16:31], v[224:227], v[144:147], v[16:31]
	ds_read_b128 v[224:227], v186 offset:16384
	v_max_f32_e32 v254, v254, v255
	v_cmp_lt_f32_e32 vcc, 0x4138aa3b, v254
	v_readlane_b32 s2, v253, 52
	s_add_i32 s36, s46, 1
	s_mul_i32 s36, s36, s56
	s_add_i32 s36, s36, s0
	s_cmp_lg_u32 s2, 0
	s_cselect_b32 s2, 1, 0
	s_cmpk_lt_i32 s36, 0x400
	s_cselect_b32 s36, 1, 0
	s_and_b32 s35, s2, s36
	s_waitcnt lgkmcnt(5)
	v_mfma_f32_32x32x16_bf16 v[0:15], v[228:231], v[144:147], v[0:15]
	ds_read_b128 v[228:231], v186 offset:20480
	s_cmp_lg_u32 s35, 0
	s_cbranch_scc0 .Lattn_pfka_s
	s_add_i32 s2, s31, 0
	s_and_b32 s2, s2, 31
	s_mul_i32 s2, s2, 0x44000
	s_add_i32 m0, s5, 0
	s_add_u32 s40, s26, s2
	s_addc_u32 s41, s27, 0
	s_add_u32 s40, s40, 0x1100000
	s_addc_u32 s41, s41, 0
	global_load_lds_dwordx4 v170, s[40:41]
	s_add_i32 m0, s5, 8192
	s_add_u32 s40, s40, 0x80
	s_addc_u32 s41, s41, 0
	global_load_lds_dwordx4 v170, s[40:41]
.Lattn_pfka_s:
	s_waitcnt lgkmcnt(5)
	v_mfma_f32_32x32x16_bf16 v[48:63], v[208:211], v[148:151], v[48:63]
	ds_read_b128 v[208:211], v186 offset:24576
	s_cmp_lg_u32 s35, 0
	s_cbranch_scc0 .Lattn_pfkb_s
	s_add_i32 s2, s31, 1
	s_and_b32 s2, s2, 31
	s_mul_i32 s2, s2, 0x44000
	s_add_i32 m0, s5, 16384
	s_add_u32 s40, s26, s2
	s_addc_u32 s41, s27, 0
	s_add_u32 s40, s40, 0x1100000
	s_addc_u32 s41, s41, 0
	global_load_lds_dwordx4 v170, s[40:41]
	s_add_i32 m0, s5, 24576
	s_add_u32 s40, s40, 0x80
	s_addc_u32 s41, s41, 0
	global_load_lds_dwordx4 v170, s[40:41]
.Lattn_pfkb_s:
	s_waitcnt lgkmcnt(5)
	v_mfma_f32_32x32x16_bf16 v[32:47], v[212:215], v[148:151], v[32:47]
	ds_read_b128 v[212:215], v186 offset:28672
	s_cmp_lg_u32 s35, 0
	s_cbranch_scc0 .Lattn_pfvt_s
	s_add_i32 s2, s31, 0
	s_and_b32 s2, s2, 31
	s_lshl_b32 s2, s2, 7
	s_add_i32 m0, s5, 65536
	s_add_u32 s44, s10, s2
	s_addc_u32 s45, s11, 0
	s_add_u32 s44, s44, 0x2000
	s_addc_u32 s45, s45, 0
	global_load_lds_dwordx4 v172, s[44:45]
	s_add_i32 m0, s5, 73728
	s_add_u32 s44, s44, 0x204000
	s_addc_u32 s45, s45, 0
	global_load_lds_dwordx4 v172, s[44:45]
.Lattn_pfvt_s:
	s_waitcnt lgkmcnt(5)
	v_mfma_f32_32x32x16_bf16 v[16:31], v[216:219], v[148:151], v[16:31]
	ds_read_b128 v[216:219], v189 offset:16384
	s_nop 0
.Lattn_sp_T30:
	v_mov_b32_e32 v255, v254
	s_nop 1
	v_permlane32_swap_b32_e32 v254, v255
	v_max_f32_e32 v254, v254, v255
	v_add_f32_e32 v180, 0x4138aa3b, v175
	v_cmp_gt_f32_e32 vcc, v254, v180
	s_nop 1
	s_waitcnt lgkmcnt(5)
	v_mfma_f32_32x32x16_bf16 v[0:15], v[220:223], v[148:151], v[0:15]
	ds_read_b128 v[220:223], v189 offset:20480
	v_cndmask_b32_e32 v180, v175, v254, vcc
	v_sub_f32_e32 v255, v175, v180
	v_exp_f32_e32 v174, v255
	v_mov_b32_e32 v175, v180
	v_sub_f32_e32 v64, v64, v175
	v_sub_f32_e32 v65, v65, v175
	v_sub_f32_e32 v66, v66, v175
	s_waitcnt lgkmcnt(5)
	v_mfma_f32_32x32x16_bf16 v[48:63], v[224:227], v[152:155], v[48:63]
	ds_read_b128 v[224:227], v189 offset:24576
	v_sub_f32_e32 v67, v67, v175
	v_sub_f32_e32 v68, v68, v175
	v_sub_f32_e32 v69, v69, v175
	v_sub_f32_e32 v70, v70, v175
	v_sub_f32_e32 v71, v71, v175
	v_exp_f32_e32 v64, v64
	v_exp_f32_e32 v65, v65
	s_waitcnt lgkmcnt(5)
	v_mfma_f32_32x32x16_bf16 v[32:47], v[228:231], v[152:155], v[32:47]
	ds_read_b128 v[228:231], v189 offset:28672
	v_exp_f32_e32 v66, v66
	v_exp_f32_e32 v67, v67
	v_exp_f32_e32 v68, v68
	v_exp_f32_e32 v69, v69
	v_exp_f32_e32 v70, v70
	v_exp_f32_e32 v71, v71
	v_add_f32_e32 v190, v64, v65
	s_waitcnt lgkmcnt(5)
	v_mfma_f32_32x32x16_bf16 v[16:31], v[208:211], v[152:155], v[16:31]
	ds_read_b128 v[208:211], v182 offset:49152
	v_add_f32_e32 v191, v66, v67
	v_add_f32_e32 v190, v190, v68
	v_add_f32_e32 v191, v191, v69
	v_add_f32_e32 v190, v190, v70
	v_add_f32_e32 v191, v191, v71
	v_cvt_pk_bf16_f32 v144, v64, v65
	v_cvt_pk_bf16_f32 v145, v66, v67
	s_waitcnt lgkmcnt(5)
	v_mfma_f32_32x32x16_bf16 v[0:15], v[212:215], v[152:155], v[0:15]
	ds_read_b128 v[212:215], v182 offset:53248
	v_cvt_pk_bf16_f32 v146, v68, v69
	v_cvt_pk_bf16_f32 v147, v70, v71
	v_sub_f32_e32 v72, v72, v175
	v_sub_f32_e32 v73, v73, v175
	v_sub_f32_e32 v74, v74, v175
	v_sub_f32_e32 v75, v75, v175
	v_sub_f32_e32 v76, v76, v175
	s_waitcnt lgkmcnt(5)
	v_mfma_f32_32x32x16_bf16 v[48:63], v[216:219], v[156:159], v[48:63]
	ds_read_b128 v[216:219], v183 offset:49152
	v_sub_f32_e32 v77, v77, v175
	v_sub_f32_e32 v78, v78, v175
	v_sub_f32_e32 v79, v79, v175
	v_exp_f32_e32 v72, v72
	v_exp_f32_e32 v73, v73
	v_exp_f32_e32 v74, v74
	v_exp_f32_e32 v75, v75
	s_waitcnt lgkmcnt(5)
	v_mfma_f32_32x32x16_bf16 v[32:47], v[220:223], v[156:159], v[32:47]
	ds_read_b128 v[220:223], v183 offset:53248
	v_exp_f32_e32 v76, v76
	v_exp_f32_e32 v77, v77
	v_exp_f32_e32 v78, v78
	v_exp_f32_e32 v79, v79
	v_add_f32_e32 v190, v190, v72
	v_add_f32_e32 v191, v191, v73
	v_add_f32_e32 v190, v190, v74
	s_waitcnt lgkmcnt(5)
	v_mfma_f32_32x32x16_bf16 v[16:31], v[224:227], v[156:159], v[16:31]
	ds_read_b128 v[224:227], v184 offset:49152
	v_add_f32_e32 v191, v191, v75
	v_add_f32_e32 v190, v190, v76
	v_add_f32_e32 v191, v191, v77
	v_add_f32_e32 v190, v190, v78
	v_add_f32_e32 v191, v191, v79
	v_cvt_pk_bf16_f32 v148, v72, v73
	v_cvt_pk_bf16_f32 v149, v74, v75
	s_waitcnt lgkmcnt(5)
	v_mfma_f32_32x32x16_bf16 v[0:15], v[228:231], v[156:159], v[0:15]
	ds_read_b128 v[228:231], v184 offset:53248
	v_cvt_pk_bf16_f32 v150, v76, v77
	v_cvt_pk_bf16_f32 v151, v78, v79
	v_sub_f32_e32 v80, v80, v175
	v_sub_f32_e32 v81, v81, v175
	v_sub_f32_e32 v82, v82, v175
	v_sub_f32_e32 v83, v83, v175
	v_sub_f32_e32 v84, v84, v175
	s_waitcnt lgkmcnt(5)
	v_mfma_f32_32x32x16_bf16 v[96:111], v[208:211], v[128:131], 0
	ds_read_b128 v[208:211], v185 offset:49152
	v_sub_f32_e32 v85, v85, v175
	v_sub_f32_e32 v86, v86, v175
	v_sub_f32_e32 v87, v87, v175
	v_exp_f32_e32 v80, v80
	v_exp_f32_e32 v81, v81
	v_exp_f32_e32 v82, v82
	v_exp_f32_e32 v83, v83
	s_waitcnt lgkmcnt(5)
	v_mfma_f32_32x32x16_bf16 v[112:127], v[212:215], v[128:131], 0
	ds_read_b128 v[212:215], v185 offset:53248
	v_exp_f32_e32 v84, v84
	v_exp_f32_e32 v85, v85
	v_exp_f32_e32 v86, v86
	v_exp_f32_e32 v87, v87
	v_add_f32_e32 v190, v190, v80
	v_add_f32_e32 v191, v191, v81
	v_add_f32_e32 v190, v190, v82
	s_waitcnt lgkmcnt(5)
	v_mfma_f32_32x32x16_bf16 v[96:111], v[216:219], v[132:135], v[96:111]
	ds_read_b128 v[216:219], v187 offset:32768
	v_add_f32_e32 v191, v191, v83
	v_add_f32_e32 v190, v190, v84
	v_add_f32_e32 v191, v191, v85
	v_add_f32_e32 v190, v190, v86
	v_add_f32_e32 v191, v191, v87
	v_cvt_pk_bf16_f32 v152, v80, v81
	v_cvt_pk_bf16_f32 v153, v82, v83
	s_waitcnt lgkmcnt(5)
	v_mfma_f32_32x32x16_bf16 v[112:127], v[220:223], v[132:135], v[112:127]
	ds_read_b128 v[220:223], v187 offset:36864
	v_cvt_pk_bf16_f32 v154, v84, v85
	v_cvt_pk_bf16_f32 v155, v86, v87
	v_sub_f32_e32 v88, v88, v175
	v_sub_f32_e32 v89, v89, v175
	v_sub_f32_e32 v90, v90, v175
	v_sub_f32_e32 v91, v91, v175
	v_sub_f32_e32 v92, v92, v175
	s_waitcnt lgkmcnt(5)
	v_mfma_f32_32x32x16_bf16 v[96:111], v[224:227], v[136:139], v[96:111]
	ds_read_b128 v[224:227], v187 offset:40960
	v_sub_f32_e32 v93, v93, v175
	v_sub_f32_e32 v94, v94, v175
	v_sub_f32_e32 v95, v95, v175
	v_exp_f32_e32 v88, v88
	v_exp_f32_e32 v89, v89
	v_exp_f32_e32 v90, v90
	v_exp_f32_e32 v91, v91
	s_waitcnt lgkmcnt(5)
	v_mfma_f32_32x32x16_bf16 v[112:127], v[228:231], v[136:139], v[112:127]
	ds_read_b128 v[228:231], v187 offset:45056
	v_exp_f32_e32 v92, v92
	v_exp_f32_e32 v93, v93
	v_exp_f32_e32 v94, v94
	v_exp_f32_e32 v95, v95
	v_add_f32_e32 v190, v190, v88
	v_add_f32_e32 v191, v191, v89
	s_waitcnt lgkmcnt(5)
	v_mfma_f32_32x32x16_bf16 v[96:111], v[208:211], v[140:143], v[96:111]
	ds_read_b128 v[208:211], v188 offset:32768
	v_add_f32_e32 v190, v190, v90
	v_add_f32_e32 v191, v191, v91
	v_add_f32_e32 v190, v190, v92
	v_add_f32_e32 v191, v191, v93
	v_add_f32_e32 v190, v190, v94
	v_add_f32_e32 v191, v191, v95
	s_waitcnt lgkmcnt(5)
	v_mfma_f32_32x32x16_bf16 v[112:127], v[212:215], v[140:143], v[112:127]
	ds_read_b128 v[212:215], v188 offset:36864
	v_cvt_pk_bf16_f32 v156, v88, v89
	v_cvt_pk_bf16_f32 v157, v90, v91
	v_cvt_pk_bf16_f32 v158, v92, v93
	v_cvt_pk_bf16_f32 v159, v94, v95
	v_add_f32_e32 v190, v190, v191
	v_fma_f32 v167, v167, v174, v190
	s_cbranch_vccz .Lattn_noresc_T30
	s_nop 7
	s_nop 7
	v_pk_mul_f32 v[0:1], v[0:1], v[174:175] op_sel_hi:[1,0]
	v_pk_mul_f32 v[2:3], v[2:3], v[174:175] op_sel_hi:[1,0]
	v_pk_mul_f32 v[4:5], v[4:5], v[174:175] op_sel_hi:[1,0]
	v_pk_mul_f32 v[6:7], v[6:7], v[174:175] op_sel_hi:[1,0]
	v_pk_mul_f32 v[8:9], v[8:9], v[174:175] op_sel_hi:[1,0]
	v_pk_mul_f32 v[10:11], v[10:11], v[174:175] op_sel_hi:[1,0]
	v_pk_mul_f32 v[12:13], v[12:13], v[174:175] op_sel_hi:[1,0]
	v_pk_mul_f32 v[14:15], v[14:15], v[174:175] op_sel_hi:[1,0]
	v_pk_mul_f32 v[16:17], v[16:17], v[174:175] op_sel_hi:[1,0]
	v_pk_mul_f32 v[18:19], v[18:19], v[174:175] op_sel_hi:[1,0]
	v_pk_mul_f32 v[20:21], v[20:21], v[174:175] op_sel_hi:[1,0]
	v_pk_mul_f32 v[22:23], v[22:23], v[174:175] op_sel_hi:[1,0]
	v_pk_mul_f32 v[24:25], v[24:25], v[174:175] op_sel_hi:[1,0]
	v_pk_mul_f32 v[26:27], v[26:27], v[174:175] op_sel_hi:[1,0]
	v_pk_mul_f32 v[28:29], v[28:29], v[174:175] op_sel_hi:[1,0]
	v_pk_mul_f32 v[30:31], v[30:31], v[174:175] op_sel_hi:[1,0]
	v_pk_mul_f32 v[32:33], v[32:33], v[174:175] op_sel_hi:[1,0]
	v_pk_mul_f32 v[34:35], v[34:35], v[174:175] op_sel_hi:[1,0]
	v_pk_mul_f32 v[36:37], v[36:37], v[174:175] op_sel_hi:[1,0]
	v_pk_mul_f32 v[38:39], v[38:39], v[174:175] op_sel_hi:[1,0]
	v_pk_mul_f32 v[40:41], v[40:41], v[174:175] op_sel_hi:[1,0]
	v_pk_mul_f32 v[42:43], v[42:43], v[174:175] op_sel_hi:[1,0]
	v_pk_mul_f32 v[44:45], v[44:45], v[174:175] op_sel_hi:[1,0]
	v_pk_mul_f32 v[46:47], v[46:47], v[174:175] op_sel_hi:[1,0]
	v_pk_mul_f32 v[48:49], v[48:49], v[174:175] op_sel_hi:[1,0]
	v_pk_mul_f32 v[50:51], v[50:51], v[174:175] op_sel_hi:[1,0]
	v_pk_mul_f32 v[52:53], v[52:53], v[174:175] op_sel_hi:[1,0]
	v_pk_mul_f32 v[54:55], v[54:55], v[174:175] op_sel_hi:[1,0]
	v_pk_mul_f32 v[56:57], v[56:57], v[174:175] op_sel_hi:[1,0]
	v_pk_mul_f32 v[58:59], v[58:59], v[174:175] op_sel_hi:[1,0]
	v_pk_mul_f32 v[60:61], v[60:61], v[174:175] op_sel_hi:[1,0]
	v_pk_mul_f32 v[62:63], v[62:63], v[174:175] op_sel_hi:[1,0]
	s_nop 1
.Lattn_noresc_T30:
.Lattn_top_T31:
	s_cmp_lg_u32 s35, 0
	s_cbranch_scc1 .Lattn_w6_slow
	s_waitcnt vmcnt(0)
	s_branch .Lattn_wd_slow

.Lattn_wd_slow:
	s_barrier
	s_waitcnt lgkmcnt(5)
	v_mfma_f32_32x32x16_bf16 v[48:63], v[216:219], v[144:147], v[48:63]
	ds_read_b128 v[216:219], v188 offset:40960
	s_nop 3
	v_max3_f32 v254, v96, v97, v98
	v_max3_f32 v255, v112, v113, v114
	v_max3_f32 v254, v254, v99, v100
	v_max3_f32 v255, v255, v115, v116
	v_max3_f32 v254, v254, v101, v102
	v_max3_f32 v255, v255, v117, v118
	v_max3_f32 v254, v254, v103, v104
	s_waitcnt lgkmcnt(5)
	v_mfma_f32_32x32x16_bf16 v[32:47], v[220:223], v[144:147], v[32:47]
	ds_read_b128 v[220:223], v188 offset:45056
	v_max3_f32 v255, v255, v119, v120
	v_max3_f32 v254, v254, v105, v106
	v_max3_f32 v255, v255, v121, v122
	v_max3_f32 v254, v254, v107, v108
	v_max3_f32 v255, v255, v123, v124
	v_max3_f32 v254, v254, v109, v110
	v_max3_f32 v255, v255, v125, v126
	v_max3_f32 v254, v254, v111, v127
	s_waitcnt lgkmcnt(5)
	v_mfma_f32_32x32x16_bf16 v[16:31], v[224:227], v[144:147], v[16:31]
	ds_read_b128 v[224:227], v186 offset:32768
	v_max_f32_e32 v254, v254, v255
	v_cmp_lt_f32_e32 vcc, 0x4138aa3b, v254
	s_cmp_lg_u32 s35, 0
	s_cbranch_scc0 .Lattn_pfq_s
	s_movk_i32 s2, 0x1100
	s_lshl_b32 s36, s14, 1
	v_mad_u32_u24 v72, v168, s2, v192
	s_add_i32 s36, s36, s30
	s_add_i32 s36, s36, 0x1100000
	s_nop 0
	v_add_u32_e32 v72, s36, v72
	s_nop 0
	global_load_dwordx4 v[64:67], v72, s[6:7]
	global_load_dwordx4 v[68:71], v72, s[6:7] offset:32
	global_load_dwordx4 v[136:139], v72, s[6:7] offset:64
	global_load_dwordx4 v[140:143], v72, s[6:7] offset:96
.Lattn_pfq_s:
	s_waitcnt lgkmcnt(5)
	v_mfma_f32_32x32x16_bf16 v[0:15], v[228:231], v[144:147], v[0:15]
	ds_read_b128 v[228:231], v186 offset:36864
	s_nop 3
.Lattn_sp_T31:
	v_mov_b32_e32 v255, v254
	s_nop 1
	v_permlane32_swap_b32_e32 v254, v255
	v_max_f32_e32 v254, v254, v255
	v_add_f32_e32 v180, 0x4138aa3b, v175
	v_cmp_gt_f32_e32 vcc, v254, v180
	s_nop 1
	v_cndmask_b32_e32 v180, v175, v254, vcc
	v_sub_f32_e32 v255, v175, v180
	v_exp_f32_e32 v174, v255
	s_waitcnt lgkmcnt(5)
	v_mfma_f32_32x32x16_bf16 v[48:63], v[208:211], v[148:151], v[48:63]
	ds_read_b128 v[208:211], v186 offset:40960
	v_mov_b32_e32 v175, v180
	v_sub_f32_e32 v96, v96, v175
	v_sub_f32_e32 v97, v97, v175
	v_sub_f32_e32 v98, v98, v175
	v_sub_f32_e32 v99, v99, v175
	v_sub_f32_e32 v100, v100, v175
	v_sub_f32_e32 v101, v101, v175
	v_sub_f32_e32 v102, v102, v175
	v_sub_f32_e32 v103, v103, v175
	v_exp_f32_e32 v96, v96
	s_waitcnt lgkmcnt(5)
	v_mfma_f32_32x32x16_bf16 v[32:47], v[212:215], v[148:151], v[32:47]
	ds_read_b128 v[212:215], v186 offset:45056
	v_exp_f32_e32 v97, v97
	v_exp_f32_e32 v98, v98
	v_exp_f32_e32 v99, v99
	v_exp_f32_e32 v100, v100
	v_exp_f32_e32 v101, v101
	v_exp_f32_e32 v102, v102
	v_exp_f32_e32 v103, v103
	v_add_f32_e32 v190, v96, v97
	v_add_f32_e32 v191, v98, v99
	v_add_f32_e32 v190, v190, v100
	s_waitcnt lgkmcnt(5)
	v_mfma_f32_32x32x16_bf16 v[16:31], v[216:219], v[148:151], v[16:31]
	ds_read_b128 v[216:219], v189 offset:32768
	v_add_f32_e32 v191, v191, v101
	v_add_f32_e32 v190, v190, v102
	v_add_f32_e32 v191, v191, v103
	v_cvt_pk_bf16_f32 v144, v96, v97
	v_cvt_pk_bf16_f32 v145, v98, v99
	v_cvt_pk_bf16_f32 v146, v100, v101
	v_cvt_pk_bf16_f32 v147, v102, v103
	s_waitcnt lgkmcnt(5)
	v_mfma_f32_32x32x16_bf16 v[0:15], v[220:223], v[148:151], v[0:15]
	ds_read_b128 v[220:223], v189 offset:36864
	v_sub_f32_e32 v104, v104, v175
	v_sub_f32_e32 v105, v105, v175
	v_sub_f32_e32 v106, v106, v175
	v_sub_f32_e32 v107, v107, v175
	v_sub_f32_e32 v108, v108, v175
	v_sub_f32_e32 v109, v109, v175
	v_sub_f32_e32 v110, v110, v175
	v_sub_f32_e32 v111, v111, v175
	v_exp_f32_e32 v104, v104
	v_exp_f32_e32 v105, v105
	s_waitcnt lgkmcnt(5)
	v_mfma_f32_32x32x16_bf16 v[48:63], v[224:227], v[152:155], v[48:63]
	ds_read_b128 v[224:227], v189 offset:40960
	v_exp_f32_e32 v106, v106
	v_exp_f32_e32 v107, v107
	v_exp_f32_e32 v108, v108
	v_exp_f32_e32 v109, v109
	v_exp_f32_e32 v110, v110
	v_exp_f32_e32 v111, v111
	v_add_f32_e32 v190, v190, v104
	v_add_f32_e32 v191, v191, v105
	v_add_f32_e32 v190, v190, v106
	v_add_f32_e32 v191, v191, v107
	s_waitcnt lgkmcnt(5)
	v_mfma_f32_32x32x16_bf16 v[32:47], v[228:231], v[152:155], v[32:47]
	ds_read_b128 v[228:231], v189 offset:45056
	v_add_f32_e32 v190, v190, v108
	v_add_f32_e32 v191, v191, v109
	v_add_f32_e32 v190, v190, v110
	v_add_f32_e32 v191, v191, v111
	v_cvt_pk_bf16_f32 v148, v104, v105
	v_cvt_pk_bf16_f32 v149, v106, v107
	v_cvt_pk_bf16_f32 v150, v108, v109
	v_cvt_pk_bf16_f32 v151, v110, v111
	s_waitcnt lgkmcnt(5)
	v_mfma_f32_32x32x16_bf16 v[16:31], v[208:211], v[152:155], v[16:31]
	ds_read_b128 v[208:211], v187 offset:49152
	s_waitcnt lgkmcnt(5)
	v_mfma_f32_32x32x16_bf16 v[0:15], v[212:215], v[152:155], v[0:15]
	ds_read_b128 v[212:215], v187 offset:53248
	v_sub_f32_e32 v112, v112, v175
	v_sub_f32_e32 v113, v113, v175
	v_sub_f32_e32 v114, v114, v175
	v_sub_f32_e32 v115, v115, v175
	v_sub_f32_e32 v116, v116, v175
	v_sub_f32_e32 v117, v117, v175
	v_sub_f32_e32 v118, v118, v175
	v_sub_f32_e32 v119, v119, v175
	v_exp_f32_e32 v112, v112
	v_exp_f32_e32 v113, v113
	v_exp_f32_e32 v114, v114
	v_exp_f32_e32 v115, v115
	s_waitcnt lgkmcnt(5)
	v_mfma_f32_32x32x16_bf16 v[48:63], v[216:219], v[156:159], v[48:63]
	ds_read_b128 v[216:219], v187 offset:57344
	v_exp_f32_e32 v116, v116
	v_exp_f32_e32 v117, v117
	v_exp_f32_e32 v118, v118
	v_exp_f32_e32 v119, v119
	v_add_f32_e32 v190, v190, v112
	v_add_f32_e32 v191, v191, v113
	v_add_f32_e32 v190, v190, v114
	v_add_f32_e32 v191, v191, v115
	v_add_f32_e32 v190, v190, v116
	v_add_f32_e32 v191, v191, v117
	v_add_f32_e32 v190, v190, v118
	v_add_f32_e32 v191, v191, v119
	s_waitcnt lgkmcnt(5)
	v_mfma_f32_32x32x16_bf16 v[32:47], v[220:223], v[156:159], v[32:47]
	ds_read_b128 v[220:223], v187 offset:61440
	v_cvt_pk_bf16_f32 v152, v112, v113
	v_cvt_pk_bf16_f32 v153, v114, v115
	v_cvt_pk_bf16_f32 v154, v116, v117
	v_cvt_pk_bf16_f32 v155, v118, v119
	s_waitcnt lgkmcnt(5)
	v_mfma_f32_32x32x16_bf16 v[16:31], v[224:227], v[156:159], v[16:31]
	ds_read_b128 v[224:227], v188 offset:49152
	s_waitcnt lgkmcnt(5)
	v_mfma_f32_32x32x16_bf16 v[0:15], v[228:231], v[156:159], v[0:15]
	ds_read_b128 v[228:231], v188 offset:53248
	v_sub_f32_e32 v120, v120, v175
	v_sub_f32_e32 v121, v121, v175
	v_sub_f32_e32 v122, v122, v175
	v_sub_f32_e32 v123, v123, v175
	v_sub_f32_e32 v124, v124, v175
	v_sub_f32_e32 v125, v125, v175
	v_sub_f32_e32 v126, v126, v175
	v_sub_f32_e32 v127, v127, v175
	v_exp_f32_e32 v120, v120
	v_exp_f32_e32 v121, v121
	v_exp_f32_e32 v122, v122
	v_exp_f32_e32 v123, v123
	v_exp_f32_e32 v124, v124
	v_exp_f32_e32 v125, v125
	v_exp_f32_e32 v126, v126
	v_exp_f32_e32 v127, v127
	v_add_f32_e32 v190, v190, v120
	v_add_f32_e32 v191, v191, v121
	v_add_f32_e32 v190, v190, v122
	v_add_f32_e32 v191, v191, v123
	v_add_f32_e32 v190, v190, v124
	v_add_f32_e32 v191, v191, v125
	v_add_f32_e32 v190, v190, v126
	v_add_f32_e32 v191, v191, v127
	v_cvt_pk_bf16_f32 v156, v120, v121
	v_cvt_pk_bf16_f32 v157, v122, v123
	v_cvt_pk_bf16_f32 v158, v124, v125
	v_cvt_pk_bf16_f32 v159, v126, v127
	v_add_f32_e32 v190, v190, v191
	v_fma_f32 v167, v167, v174, v190
	s_cbranch_vccz .Lattn_noresc_T31
	s_nop 7
	s_nop 7
	v_pk_mul_f32 v[0:1], v[0:1], v[174:175] op_sel_hi:[1,0]
	v_pk_mul_f32 v[2:3], v[2:3], v[174:175] op_sel_hi:[1,0]
	v_pk_mul_f32 v[4:5], v[4:5], v[174:175] op_sel_hi:[1,0]
	v_pk_mul_f32 v[6:7], v[6:7], v[174:175] op_sel_hi:[1,0]
	v_pk_mul_f32 v[8:9], v[8:9], v[174:175] op_sel_hi:[1,0]
	v_pk_mul_f32 v[10:11], v[10:11], v[174:175] op_sel_hi:[1,0]
	v_pk_mul_f32 v[12:13], v[12:13], v[174:175] op_sel_hi:[1,0]
	v_pk_mul_f32 v[14:15], v[14:15], v[174:175] op_sel_hi:[1,0]
	v_pk_mul_f32 v[16:17], v[16:17], v[174:175] op_sel_hi:[1,0]
	v_pk_mul_f32 v[18:19], v[18:19], v[174:175] op_sel_hi:[1,0]
	v_pk_mul_f32 v[20:21], v[20:21], v[174:175] op_sel_hi:[1,0]
	v_pk_mul_f32 v[22:23], v[22:23], v[174:175] op_sel_hi:[1,0]
	v_pk_mul_f32 v[24:25], v[24:25], v[174:175] op_sel_hi:[1,0]
	v_pk_mul_f32 v[26:27], v[26:27], v[174:175] op_sel_hi:[1,0]
	v_pk_mul_f32 v[28:29], v[28:29], v[174:175] op_sel_hi:[1,0]
	v_pk_mul_f32 v[30:31], v[30:31], v[174:175] op_sel_hi:[1,0]
	v_pk_mul_f32 v[32:33], v[32:33], v[174:175] op_sel_hi:[1,0]
	v_pk_mul_f32 v[34:35], v[34:35], v[174:175] op_sel_hi:[1,0]
	v_pk_mul_f32 v[36:37], v[36:37], v[174:175] op_sel_hi:[1,0]
	v_pk_mul_f32 v[38:39], v[38:39], v[174:175] op_sel_hi:[1,0]
	v_pk_mul_f32 v[40:41], v[40:41], v[174:175] op_sel_hi:[1,0]
	v_pk_mul_f32 v[42:43], v[42:43], v[174:175] op_sel_hi:[1,0]
	v_pk_mul_f32 v[44:45], v[44:45], v[174:175] op_sel_hi:[1,0]
	v_pk_mul_f32 v[46:47], v[46:47], v[174:175] op_sel_hi:[1,0]
	v_pk_mul_f32 v[48:49], v[48:49], v[174:175] op_sel_hi:[1,0]
	v_pk_mul_f32 v[50:51], v[50:51], v[174:175] op_sel_hi:[1,0]
	v_pk_mul_f32 v[52:53], v[52:53], v[174:175] op_sel_hi:[1,0]
	v_pk_mul_f32 v[54:55], v[54:55], v[174:175] op_sel_hi:[1,0]
	v_pk_mul_f32 v[56:57], v[56:57], v[174:175] op_sel_hi:[1,0]
	v_pk_mul_f32 v[58:59], v[58:59], v[174:175] op_sel_hi:[1,0]
	v_pk_mul_f32 v[60:61], v[60:61], v[174:175] op_sel_hi:[1,0]
	v_pk_mul_f32 v[62:63], v[62:63], v[174:175] op_sel_hi:[1,0]
	s_nop 1

	.amdhsa_kernel _Z14fwd_megakernelILb1EEv6Params
		.amdhsa_group_segment_fixed_size 16384
		.amdhsa_private_segment_fixed_size 0
		.amdhsa_kernarg_size 384
		.amdhsa_user_sgpr_count 2
		.amdhsa_user_sgpr_dispatch_ptr 0
		.amdhsa_user_sgpr_queue_ptr 0
		.amdhsa_user_sgpr_kernarg_segment_ptr 1
		.amdhsa_user_sgpr_dispatch_id 0
		.amdhsa_user_sgpr_kernarg_preload_length 0
		.amdhsa_user_sgpr_kernarg_preload_offset 0
		.amdhsa_user_sgpr_private_segment_size 0
		.amdhsa_uses_dynamic_stack 0
		.amdhsa_enable_private_segment 0
		.amdhsa_system_sgpr_workgroup_id_x 1
		.amdhsa_system_sgpr_workgroup_id_y 0
		.amdhsa_system_sgpr_workgroup_id_z 0
		.amdhsa_system_sgpr_workgroup_info 0
		.amdhsa_system_vgpr_workitem_id 2
		.amdhsa_next_free_vgpr 256
		.amdhsa_next_free_sgpr 100
		.amdhsa_accum_offset 256
		.amdhsa_reserve_vcc 1
		.amdhsa_float_round_mode_32 0
		.amdhsa_float_round_mode_16_64 0
		.amdhsa_float_denorm_mode_32 3
		.amdhsa_float_denorm_mode_16_64 3
		.amdhsa_dx10_clamp 1
		.amdhsa_ieee_mode 1
		.amdhsa_fp16_overflow 0
		.amdhsa_tg_split 0
		.amdhsa_exception_fp_ieee_invalid_op 0
		.amdhsa_exception_fp_denorm_src 0
		.amdhsa_exception_fp_ieee_div_zero 0
		.amdhsa_exception_fp_ieee_overflow 0
		.amdhsa_exception_fp_ieee_underflow 0
		.amdhsa_exception_fp_ieee_inexact 0
		.amdhsa_exception_int_div_zero 0
	.end_amdhsa_kernel

amdhsa.kernels:
  - .agpr_count:     0
    .args:
      - .offset:         0
        .size:           128
        .value_kind:     by_value
      - .offset:         128
        .size:           4
        .value_kind:     hidden_block_count_x
      - .offset:         132
        .size:           4
        .value_kind:     hidden_block_count_y
      - .offset:         136
        .size:           4
        .value_kind:     hidden_block_count_z
      - .offset:         140
        .size:           2
        .value_kind:     hidden_group_size_x
      - .offset:         142
        .size:           2
        .value_kind:     hidden_group_size_y
      - .offset:         144
        .size:           2
        .value_kind:     hidden_group_size_z
      - .offset:         146
        .size:           2
        .value_kind:     hidden_remainder_x
      - .offset:         148
        .size:           2
        .value_kind:     hidden_remainder_y
      - .offset:         150
        .size:           2
        .value_kind:     hidden_remainder_z
      - .offset:         168
        .size:           8
        .value_kind:     hidden_global_offset_x
      - .offset:         176
        .size:           8
        .value_kind:     hidden_global_offset_y
      - .offset:         184
        .size:           8
        .value_kind:     hidden_global_offset_z
      - .offset:         192
        .size:           2
        .value_kind:     hidden_grid_dims
      - .offset:         216
        .size:           8
        .value_kind:     hidden_multigrid_sync_arg
      - .offset:         248
        .size:           4
        .value_kind:     hidden_dynamic_lds_size
    .group_segment_fixed_size: 16384
    .kernarg_segment_align: 8
    .kernarg_segment_size: 384
    .language:       OpenCL C
    .language_version:
      - 2
      - 0
    .max_flat_workgroup_size: 512
    .name:           _Z14fwd_megakernelILb1EEv6Params
    .private_segment_fixed_size: 0
    .sgpr_count:     106
    .sgpr_spill_count: 87
    .symbol:         _Z14fwd_megakernelILb1EEv6Params.kd
    .uniform_work_group_size: 1
    .uses_dynamic_stack: false
    .vgpr_count:     256
    .vgpr_spill_count: 0
    .wavefront_size: 64
  - .agpr_count:     0
    .args:
      - .offset:         0
        .size:           128
        .value_kind:     by_value
      - .offset:         128
        .size:           4
        .value_kind:     hidden_block_count_x
      - .offset:         132
        .size:           4
        .value_kind:     hidden_block_count_y
      - .offset:         136
        .size:           4
        .value_kind:     hidden_block_count_z
      - .offset:         140
        .size:           2
        .value_kind:     hidden_group_size_x
      - .offset:         142
        .size:           2
        .value_kind:     hidden_group_size_y
      - .offset:         144
        .size:           2
        .value_kind:     hidden_group_size_z
      - .offset:         146
        .size:           2
        .value_kind:     hidden_remainder_x
      - .offset:         148
        .size:           2
        .value_kind:     hidden_remainder_y
      - .offset:         150
        .size:           2
        .value_kind:     hidden_remainder_z
      - .offset:         168
        .size:           8
        .value_kind:     hidden_global_offset_x
      - .offset:         176
        .size:           8
        .value_kind:     hidden_global_offset_y
      - .offset:         184
        .size:           8
        .value_kind:     hidden_global_offset_z
      - .offset:         192
        .size:           2
        .value_kind:     hidden_grid_dims
      - .offset:         216
        .size:           8
        .value_kind:     hidden_multigrid_sync_arg
      - .offset:         248
        .size:           4
        .value_kind:     hidden_dynamic_lds_size
    .group_segment_fixed_size: 0
    .kernarg_segment_align: 8
    .kernarg_segment_size: 384
    .language:       OpenCL C
    .language_version:
      - 2
      - 0
    .max_flat_workgroup_size: 512
    .name:           _Z14fwd_megakernelILb0EEv6Params
    .private_segment_fixed_size: 0
    .sgpr_count:     106
    .sgpr_spill_count: 88
    .symbol:         _Z14fwd_megakernelILb0EEv6Params.kd
    .uniform_work_group_size: 1
    .uses_dynamic_stack: false
    .vgpr_count:     246
    .vgpr_spill_count: 0
    .wavefront_size: 64
